# on top: gemm_in v_a/v_d tiles transposed through wave-private LDS and stored as 16-byte row pieces; scan final-state unit loads batched; LDS fragment reads hoisted in the two peeled latent-attention t
# speedup vs baseline: 1.0083x; 1.0036x over previous
.LBB0_121:
	s_cmpk_gt_i32 s12, 0x1ff
	s_mov_b64 s[4:5], -1
	s_cbranch_scc0 .LBB0_123
	s_add_i32 s0, s12, 0xfffffe00
	s_lshr_b32 s0, s0, 3
	s_and_b32 s13, s12, 1
	s_and_b32 s15, s0, 0x1ffffffe
	s_or_b32 s5, s15, s13
	s_bfe_u32 s14, s12, 0x30001
	s_lshl_b32 s0, s5, 3
	s_or_b32 s0, s0, s14
	s_xor_b32 s4, s0, 8
	s_lshl_b32 s0, s4, 1
	s_or_b32 s0, s0, s13
	s_lshl_b64 s[6:7], s[0:1], 2
	v_readlane_b32 s8, v253, 62
	v_readlane_b32 s9, v253, 63
	s_add_u32 s8, s8, s6
	s_addc_u32 s9, s9, s7
	s_lshl_b32 s0, s5, 4
	s_lshl_b32 s5, s14, 1
	s_or_b32 s0, s0, s5
	s_or_b32 s0, s0, s13
	s_lshl_b64 s[6:7], s[0:1], 14
	s_add_u32 s6, s30, s6
	s_mov_b32 s5, s1
	s_addc_u32 s7, s31, s7
	s_lshl_b64 s[4:5], s[4:5], 15
	s_add_u32 s0, s30, s4
	s_addc_u32 s5, s31, s5
	s_lshl_b32 s4, s13, 14
	s_add_u32 s4, s0, s4
	s_addc_u32 s5, s5, 0
	v_lshlrev_b64 v[2:3], 1, v[8:9]
	v_lshl_add_u64 v[28:29], s[6:7], 0, v[2:3]
	v_lshl_add_u64 v[2:3], s[4:5], 0, v[2:3]
	global_load_dword v0, v169, s[8:9]
	v_lshlrev_b32_e32 v222, 1, v8
	v_lshlrev_b32_e32 v223, 1, v10
	v_lshlrev_b32_e32 v224, 1, v12
	v_lshlrev_b32_e32 v225, 1, v14
	v_lshlrev_b32_e32 v226, 1, v16
	v_lshlrev_b32_e32 v227, 1, v18
	v_lshlrev_b32_e32 v228, 1, v20
	v_lshlrev_b32_e32 v229, 1, v22
	global_load_dwordx2 v[176:177], v222, s[6:7]
	global_load_dwordx2 v[178:179], v222, s[4:5]
	global_load_dwordx2 v[180:181], v223, s[6:7]
	global_load_dwordx2 v[182:183], v223, s[4:5]
	global_load_dwordx2 v[184:185], v224, s[6:7]
	global_load_dwordx2 v[186:187], v224, s[4:5]
	global_load_dwordx2 v[188:189], v225, s[6:7]
	global_load_dwordx2 v[190:191], v225, s[4:5]
	global_load_dwordx2 v[192:193], v226, s[6:7]
	global_load_dwordx2 v[194:195], v226, s[4:5]
	global_load_dwordx2 v[196:197], v227, s[6:7]
	global_load_dwordx2 v[198:199], v227, s[4:5]
	global_load_dwordx2 v[200:201], v228, s[6:7]
	global_load_dwordx2 v[202:203], v228, s[4:5]
	global_load_dwordx2 v[204:205], v229, s[6:7]
	global_load_dwordx2 v[206:207], v229, s[4:5]
	s_cmp_eq_u32 s13, 0
	s_brev_b32 s0, 48
	s_cselect_b32 s0, s0, 0xd000000
	s_add_u32 s0, s94, s0
	v_readlane_b32 s8, v255, 43
	s_addc_u32 s13, s95, 0
	s_add_i32 s15, s15, s8
	s_lshl_b32 s8, s15, 3
	v_readlane_b32 s9, v255, 44
	s_or_b32 s8, s8, s14
	s_ashr_i32 s9, s8, 31
	s_lshl_b64 s[8:9], s[8:9], 15
	s_add_u32 s8, s0, s8
	s_addc_u32 s9, s13, s9
	v_lshlrev_b32_e32 v234, 2, v8
	v_lshlrev_b32_e32 v235, 2, v10
	v_lshlrev_b32_e32 v236, 2, v12
	v_lshlrev_b32_e32 v237, 2, v14
	v_lshlrev_b32_e32 v238, 2, v16
	v_lshlrev_b32_e32 v239, 2, v18
	v_lshlrev_b32_e32 v240, 2, v20
	v_lshlrev_b32_e32 v241, 2, v22
	s_waitcnt vmcnt(14)
	v_cvt_f32_f16_e32 v24, v176
	v_cvt_f32_f16_sdwa v25, v176 dst_sel:DWORD dst_unused:UNUSED_PAD src0_sel:WORD_1
	v_cvt_f32_f16_e32 v26, v177
	v_cvt_f32_f16_sdwa v27, v177 dst_sel:DWORD dst_unused:UNUSED_PAD src0_sel:WORD_1
	v_cvt_f32_f16_e32 v30, v178
	v_cvt_f32_f16_sdwa v31, v178 dst_sel:DWORD dst_unused:UNUSED_PAD src0_sel:WORD_1
	v_cvt_f32_f16_e32 v34, v179
	v_cvt_f32_f16_sdwa v35, v179 dst_sel:DWORD dst_unused:UNUSED_PAD src0_sel:WORD_1
	v_pk_fma_f32 v[24:25], v[0:1], v[24:25], v[30:31] op_sel_hi:[0,1,1]
	v_pk_fma_f32 v[26:27], v[0:1], v[26:27], v[34:35] op_sel_hi:[0,1,1]
	global_store_dwordx4 v234, v[24:27], s[8:9]
	s_waitcnt vmcnt(13)
	v_cvt_f32_f16_e32 v230, v180
	v_cvt_f32_f16_sdwa v231, v180 dst_sel:DWORD dst_unused:UNUSED_PAD src0_sel:WORD_1
	v_cvt_f32_f16_e32 v232, v181
	v_cvt_f32_f16_sdwa v233, v181 dst_sel:DWORD dst_unused:UNUSED_PAD src0_sel:WORD_1
	v_cvt_f32_f16_e32 v30, v182
	v_cvt_f32_f16_sdwa v31, v182 dst_sel:DWORD dst_unused:UNUSED_PAD src0_sel:WORD_1
	v_cvt_f32_f16_e32 v34, v183
	v_cvt_f32_f16_sdwa v35, v183 dst_sel:DWORD dst_unused:UNUSED_PAD src0_sel:WORD_1
	v_pk_fma_f32 v[230:231], v[0:1], v[230:231], v[30:31] op_sel_hi:[0,1,1]
	v_pk_fma_f32 v[232:233], v[0:1], v[232:233], v[34:35] op_sel_hi:[0,1,1]
	global_store_dwordx4 v235, v[230:233], s[8:9]
	s_waitcnt vmcnt(12)
	v_cvt_f32_f16_e32 v24, v184
	v_cvt_f32_f16_sdwa v25, v184 dst_sel:DWORD dst_unused:UNUSED_PAD src0_sel:WORD_1
	v_cvt_f32_f16_e32 v26, v185
	v_cvt_f32_f16_sdwa v27, v185 dst_sel:DWORD dst_unused:UNUSED_PAD src0_sel:WORD_1
	v_cvt_f32_f16_e32 v30, v186
	v_cvt_f32_f16_sdwa v31, v186 dst_sel:DWORD dst_unused:UNUSED_PAD src0_sel:WORD_1
	v_cvt_f32_f16_e32 v34, v187
	v_cvt_f32_f16_sdwa v35, v187 dst_sel:DWORD dst_unused:UNUSED_PAD src0_sel:WORD_1
	v_pk_fma_f32 v[24:25], v[0:1], v[24:25], v[30:31] op_sel_hi:[0,1,1]
	v_pk_fma_f32 v[26:27], v[0:1], v[26:27], v[34:35] op_sel_hi:[0,1,1]
	global_store_dwordx4 v236, v[24:27], s[8:9]
	s_waitcnt vmcnt(11)
	v_cvt_f32_f16_e32 v230, v188
	v_cvt_f32_f16_sdwa v231, v188 dst_sel:DWORD dst_unused:UNUSED_PAD src0_sel:WORD_1
	v_cvt_f32_f16_e32 v232, v189
	v_cvt_f32_f16_sdwa v233, v189 dst_sel:DWORD dst_unused:UNUSED_PAD src0_sel:WORD_1
	v_cvt_f32_f16_e32 v30, v190
	v_cvt_f32_f16_sdwa v31, v190 dst_sel:DWORD dst_unused:UNUSED_PAD src0_sel:WORD_1
	v_cvt_f32_f16_e32 v34, v191
	v_cvt_f32_f16_sdwa v35, v191 dst_sel:DWORD dst_unused:UNUSED_PAD src0_sel:WORD_1
	v_pk_fma_f32 v[230:231], v[0:1], v[230:231], v[30:31] op_sel_hi:[0,1,1]
	v_pk_fma_f32 v[232:233], v[0:1], v[232:233], v[34:35] op_sel_hi:[0,1,1]
	global_store_dwordx4 v237, v[230:233], s[8:9]
	s_waitcnt vmcnt(10)
	v_cvt_f32_f16_e32 v24, v192
	v_cvt_f32_f16_sdwa v25, v192 dst_sel:DWORD dst_unused:UNUSED_PAD src0_sel:WORD_1
	v_cvt_f32_f16_e32 v26, v193
	v_cvt_f32_f16_sdwa v27, v193 dst_sel:DWORD dst_unused:UNUSED_PAD src0_sel:WORD_1
	v_cvt_f32_f16_e32 v30, v194
	v_cvt_f32_f16_sdwa v31, v194 dst_sel:DWORD dst_unused:UNUSED_PAD src0_sel:WORD_1
	v_cvt_f32_f16_e32 v34, v195
	v_cvt_f32_f16_sdwa v35, v195 dst_sel:DWORD dst_unused:UNUSED_PAD src0_sel:WORD_1
	v_pk_fma_f32 v[24:25], v[0:1], v[24:25], v[30:31] op_sel_hi:[0,1,1]
	v_pk_fma_f32 v[26:27], v[0:1], v[26:27], v[34:35] op_sel_hi:[0,1,1]
	global_store_dwordx4 v238, v[24:27], s[8:9]
	s_waitcnt vmcnt(9)
	v_cvt_f32_f16_e32 v230, v196
	v_cvt_f32_f16_sdwa v231, v196 dst_sel:DWORD dst_unused:UNUSED_PAD src0_sel:WORD_1
	v_cvt_f32_f16_e32 v232, v197
	v_cvt_f32_f16_sdwa v233, v197 dst_sel:DWORD dst_unused:UNUSED_PAD src0_sel:WORD_1
	v_cvt_f32_f16_e32 v30, v198
	v_cvt_f32_f16_sdwa v31, v198 dst_sel:DWORD dst_unused:UNUSED_PAD src0_sel:WORD_1
	v_cvt_f32_f16_e32 v34, v199
	v_cvt_f32_f16_sdwa v35, v199 dst_sel:DWORD dst_unused:UNUSED_PAD src0_sel:WORD_1
	v_pk_fma_f32 v[230:231], v[0:1], v[230:231], v[30:31] op_sel_hi:[0,1,1]
	v_pk_fma_f32 v[232:233], v[0:1], v[232:233], v[34:35] op_sel_hi:[0,1,1]
	global_store_dwordx4 v239, v[230:233], s[8:9]
	s_waitcnt vmcnt(8)
	v_cvt_f32_f16_e32 v24, v200
	v_cvt_f32_f16_sdwa v25, v200 dst_sel:DWORD dst_unused:UNUSED_PAD src0_sel:WORD_1
	v_cvt_f32_f16_e32 v26, v201
	v_cvt_f32_f16_sdwa v27, v201 dst_sel:DWORD dst_unused:UNUSED_PAD src0_sel:WORD_1
	v_cvt_f32_f16_e32 v30, v202
	v_cvt_f32_f16_sdwa v31, v202 dst_sel:DWORD dst_unused:UNUSED_PAD src0_sel:WORD_1
	v_cvt_f32_f16_e32 v34, v203
	v_cvt_f32_f16_sdwa v35, v203 dst_sel:DWORD dst_unused:UNUSED_PAD src0_sel:WORD_1
	v_pk_fma_f32 v[24:25], v[0:1], v[24:25], v[30:31] op_sel_hi:[0,1,1]
	v_pk_fma_f32 v[26:27], v[0:1], v[26:27], v[34:35] op_sel_hi:[0,1,1]
	global_store_dwordx4 v240, v[24:27], s[8:9]
	s_waitcnt vmcnt(7)
	v_cvt_f32_f16_e32 v230, v204
	v_cvt_f32_f16_sdwa v231, v204 dst_sel:DWORD dst_unused:UNUSED_PAD src0_sel:WORD_1
	v_cvt_f32_f16_e32 v232, v205
	v_cvt_f32_f16_sdwa v233, v205 dst_sel:DWORD dst_unused:UNUSED_PAD src0_sel:WORD_1
	v_cvt_f32_f16_e32 v30, v206
	v_cvt_f32_f16_sdwa v31, v206 dst_sel:DWORD dst_unused:UNUSED_PAD src0_sel:WORD_1
	v_cvt_f32_f16_e32 v34, v207
	v_cvt_f32_f16_sdwa v35, v207 dst_sel:DWORD dst_unused:UNUSED_PAD src0_sel:WORD_1
	v_pk_fma_f32 v[230:231], v[0:1], v[230:231], v[30:31] op_sel_hi:[0,1,1]
	v_pk_fma_f32 v[232:233], v[0:1], v[232:233], v[34:35] op_sel_hi:[0,1,1]
	global_store_dwordx4 v241, v[230:233], s[8:9]
	s_mov_b64 s[4:5], 0

.LBB0_129:
	s_waitcnt vmcnt(7)
	ds_write_b128 v124, v[16:19] offset:17408
	s_waitcnt vmcnt(6)
	ds_write_b128 v124, v[20:23] offset:21760
	s_waitcnt vmcnt(5)
	ds_write_b128 v124, v[24:27] offset:26112
	s_waitcnt vmcnt(4)
	ds_write_b128 v124, v[28:31] offset:30464
	s_waitcnt vmcnt(3)
	ds_write_b128 v126, v[32:35] offset:53248
	s_waitcnt vmcnt(2)
	ds_write_b128 v126, v[36:39] offset:57856
	s_waitcnt vmcnt(1)
	ds_write_b128 v126, v[40:43] offset:62464
	s_waitcnt vmcnt(0)
	ds_write_b128 v111, v[44:47] offset:32256
	v_add_u32_e32 v81, v122, v113
	ds_read_b128 v[128:131], v81
	ds_read_b128 v[132:135], v81 offset:64
	ds_read_b128 v[136:139], v81 offset:4416
	ds_read_b128 v[140:143], v81 offset:8768
	ds_read_b128 v[144:147], v81 offset:13120
	ds_read_b128 v[148:151], v81 offset:128
	ds_read_b128 v[152:155], v81 offset:192
	s_waitcnt lgkmcnt(14)
	ds_read_b128 v[156:159], v81 offset:4352
	s_waitcnt lgkmcnt(14)
	ds_read_b128 v[160:163], v81 offset:4480
	s_waitcnt lgkmcnt(14)
	ds_read_b128 v[164:167], v81 offset:4544
	s_waitcnt lgkmcnt(14)
	ds_read_b128 v[176:179], v81 offset:8704
	s_waitcnt lgkmcnt(14)
	ds_read_b128 v[180:183], v81 offset:8832
	s_nop 0
	s_nop 0
	s_waitcnt lgkmcnt(14)
	s_mov_b32 s4, 0xf149f2ca
	s_mov_b32 s0, 0x3db504f3
	s_mov_b32 s2, 0xf149f2ca
	s_movk_i32 s68, 0xff
	s_waitcnt lgkmcnt(14)
	s_waitcnt lgkmcnt(11)
	v_mfma_f32_16x16x32_f16 v[16:19], v[128:131], v[12:15], 0
	ds_read_b128 v[128:131], v81 offset:8896
	s_nop 0
	s_nop 0
	s_nop 0
	s_nop 0
	s_waitcnt lgkmcnt(11)
	v_mfma_f32_16x16x32_f16 v[16:19], v[132:135], v[8:11], v[16:19]
	ds_read_b128 v[132:135], v81 offset:13056
	s_nop 0
	s_nop 0
	s_waitcnt lgkmcnt(8)
	v_mfma_f32_16x16x32_f16 v[16:19], v[148:151], v[4:7], v[16:19]
	ds_read_b128 v[148:151], v81 offset:13184
	s_nop 0
	s_nop 0
	s_waitcnt lgkmcnt(8)
	v_mfma_f32_16x16x32_f16 v[16:19], v[152:155], v[0:3], v[16:19]
	s_nop 0
	s_nop 0
	s_waitcnt lgkmcnt(7)
	v_mfma_f32_16x16x32_f16 v[20:23], v[156:159], v[12:15], 0
	v_mfma_f32_16x16x32_f16 v[20:23], v[136:139], v[8:11], v[20:23]
	s_nop 0
	s_nop 0
	s_waitcnt lgkmcnt(6)
	v_mfma_f32_16x16x32_f16 v[20:23], v[160:163], v[4:7], v[20:23]
	s_nop 0
	s_nop 0
	s_waitcnt lgkmcnt(5)
	v_mfma_f32_16x16x32_f16 v[20:23], v[164:167], v[0:3], v[20:23]
	s_nop 0
	s_nop 6
	v_mul_f32_e32 v36, 0x3db504f3, v20
	s_nop 0
	s_waitcnt lgkmcnt(4)
	v_mfma_f32_16x16x32_f16 v[24:27], v[176:179], v[12:15], 0
	v_mul_f32_e32 v37, 0x3db504f3, v21
	v_mul_f32_e32 v38, 0x3db504f3, v22
	v_mul_f32_e32 v39, 0x3db504f3, v23
	v_mfma_f32_16x16x32_f16 v[24:27], v[140:143], v[8:11], v[24:27]
	s_nop 0
	s_nop 0
	s_waitcnt lgkmcnt(3)
	v_mfma_f32_16x16x32_f16 v[24:27], v[180:183], v[4:7], v[24:27]
	s_nop 0
	s_nop 0
	s_waitcnt lgkmcnt(2)
	v_mfma_f32_16x16x32_f16 v[24:27], v[128:131], v[0:3], v[24:27]
	s_nop 0
	s_nop 6
	v_mul_f32_e32 v40, 0x3db504f3, v24
	s_nop 0
	s_waitcnt lgkmcnt(1)
	v_mfma_f32_16x16x32_f16 v[28:31], v[132:135], v[12:15], 0
	v_mul_f32_e32 v41, 0x3db504f3, v25
	v_mul_f32_e32 v42, 0x3db504f3, v26
	v_mul_f32_e32 v43, 0x3db504f3, v27
	v_mfma_f32_16x16x32_f16 v[28:31], v[144:147], v[8:11], v[28:31]
	s_nop 0
	s_nop 0
	s_waitcnt lgkmcnt(0)
	v_mfma_f32_16x16x32_f16 v[28:31], v[148:151], v[4:7], v[28:31]
	ds_read_b128 v[32:35], v81 offset:13248
	s_nop 0
	s_waitcnt lgkmcnt(0)
	v_mfma_f32_16x16x32_f16 v[28:31], v[32:35], v[0:3], v[28:31]
	v_mul_f32_e32 v32, 0x3db504f3, v16
	v_mul_f32_e32 v33, 0x3db504f3, v17
	v_mul_f32_e32 v34, 0x3db504f3, v18
	v_mul_f32_e32 v35, 0x3db504f3, v19
	v_max3_f32 v32, v32, s4, v33
	v_max3_f32 v32, v32, v34, v35
	v_max3_f32 v32, v32, v36, v37
	v_max3_f32 v32, v32, v38, v39
	v_max3_f32 v32, v32, v40, v41
	v_mul_f32_e32 v44, 0x3db504f3, v28
	v_mul_f32_e32 v45, 0x3db504f3, v29
	v_max3_f32 v32, v32, v42, v43
	v_mul_f32_e32 v46, 0x3db504f3, v30
	v_mul_f32_e32 v47, 0x3db504f3, v31
	v_max3_f32 v32, v32, v44, v45
	v_max3_f32 v32, v32, v46, v47
	ds_bpermute_b32 v33, v117, v32
	s_nop 0
	s_waitcnt lgkmcnt(0)
	v_max_f32_e32 v33, v33, v33
	v_max_f32_e32 v32, v32, v33
	ds_bpermute_b32 v33, v119, v32
	s_nop 0
	s_waitcnt lgkmcnt(0)
	v_max3_f32 v83, v85, v32, v33
	v_fma_f32 v16, v16, s0, -v83
	v_mul_f32_e32 v16, 0x3fb8aa3b, v16
	v_fma_f32 v17, v17, s0, -v83
	v_sub_f32_e32 v32, v85, v83
	v_exp_f32_e32 v85, v16
	v_mul_f32_e32 v17, 0x3fb8aa3b, v17
	v_exp_f32_e32 v89, v17
	v_mul_f32_e32 v32, 0x3fb8aa3b, v32
	v_add_f32_e32 v16, 0, v85
	v_add_f32_e32 v168, v89, v16
	v_fma_f32 v16, v18, s0, -v83
	v_mul_f32_e32 v16, 0x3fb8aa3b, v16
	v_exp_f32_e32 v94, v16
	v_fma_f32 v16, v19, s0, -v83
	v_mul_f32_e32 v16, 0x3fb8aa3b, v16
	v_exp_f32_e32 v96, v16
	v_fma_f32 v16, v20, s0, -v83
	v_mul_f32_e32 v16, 0x3fb8aa3b, v16
	v_exp_f32_e32 v98, v16
	v_fma_f32 v16, v21, s0, -v83
	v_mul_f32_e32 v16, 0x3fb8aa3b, v16
	v_exp_f32_e32 v104, v16
	v_fma_f32 v16, v22, s0, -v83
	v_mul_f32_e32 v16, 0x3fb8aa3b, v16
	v_exp_f32_e32 v106, v16
	v_fma_f32 v16, v23, s0, -v83
	v_mul_f32_e32 v16, 0x3fb8aa3b, v16
	v_exp_f32_e32 v108, v16
	v_fma_f32 v16, v24, s0, -v83
	v_mul_f32_e32 v16, 0x3fb8aa3b, v16
	v_exp_f32_e32 v110, v16
	v_fma_f32 v16, v25, s0, -v83
	v_mul_f32_e32 v16, 0x3fb8aa3b, v16
	v_exp_f32_e32 v112, v16
	v_fma_f32 v16, v26, s0, -v83
	v_mul_f32_e32 v16, 0x3fb8aa3b, v16
	v_exp_f32_e32 v80, v16
	v_fma_f32 v16, v27, s0, -v83
	v_mul_f32_e32 v16, 0x3fb8aa3b, v16
	v_exp_f32_e32 v82, v16
	v_fma_f32 v16, v28, s0, -v83
	v_mul_f32_e32 v16, 0x3fb8aa3b, v16
	v_exp_f32_e32 v84, v16
	v_fma_f32 v16, v29, s0, -v83
	v_mul_f32_e32 v16, 0x3fb8aa3b, v16
	v_exp_f32_e32 v86, v16
	v_fma_f32 v16, v30, s0, -v83
	v_mul_f32_e32 v16, 0x3fb8aa3b, v16
	v_exp_f32_e32 v88, v16
	v_fma_f32 v16, v31, s0, -v83
	v_mul_f32_e32 v16, 0x3fb8aa3b, v16
	v_exp_f32_e32 v90, v16
	v_exp_f32_e32 v16, v32
	s_nop 0
	v_pk_mul_f32 v[36:37], v[56:57], v[16:17] op_sel_hi:[1,0]
	v_add_u32_e32 v57, v105, v107
	v_add_u32_e32 v56, 0x8800, v57
	ds_read2_b64 v[152:155], v56 offset1:4
	v_pk_mul_f32 v[42:43], v[54:55], v[16:17] op_sel_hi:[1,0]
	v_pk_mul_f32 v[40:41], v[52:53], v[16:17] op_sel_hi:[1,0]
	s_nop 0
	v_pk_mul_f32 v[46:47], v[50:51], v[16:17] op_sel_hi:[1,0]
	v_pk_mul_f32 v[44:45], v[48:49], v[16:17] op_sel_hi:[1,0]
	v_pk_mul_f32 v[26:27], v[70:71], v[16:17] op_sel_hi:[1,0]
	v_cvt_pk_f16_f32 v51, v106, v108
	v_cvt_pk_f16_f32 v50, v98, v104
	v_cvt_pk_f16_f32 v49, v94, v96
	v_cvt_pk_f16_f32 v48, v85, v89
	v_add_u32_e32 v70, 0x9000, v57
	ds_read2_b64 v[156:159], v70 offset0:32 offset1:36
	v_add_u32_e32 v71, 0x9800, v57
	ds_read2_b64 v[136:139], v71 offset0:64 offset1:68
	s_nop 0
	s_waitcnt lgkmcnt(2)
	v_mfma_f32_16x16x32_f16 v[44:47], v[152:155], v[48:51], v[44:47]
	s_nop 0
	v_pk_mul_f32 v[38:39], v[58:59], v[16:17] op_sel_hi:[1,0]
	v_pk_mul_f32 v[20:21], v[72:73], v[16:17] op_sel_hi:[1,0]
	s_nop 0
	s_waitcnt lgkmcnt(1)
	v_mfma_f32_16x16x32_f16 v[40:43], v[156:159], v[48:51], v[40:43]
	s_nop 0
	v_add_u32_e32 v72, 0xa000, v57
	ds_read2_b64 v[160:163], v72 offset0:96 offset1:100
	v_pk_mul_f32 v[34:35], v[62:63], v[16:17] op_sel_hi:[1,0]
	s_nop 0
	s_waitcnt lgkmcnt(1)
	v_mfma_f32_16x16x32_f16 v[36:39], v[136:139], v[48:51], v[36:39]
	s_nop 0
	v_pk_mul_f32 v[32:33], v[60:61], v[16:17] op_sel_hi:[1,0]
	v_add_u32_e32 v73, 0xa800, v57
	ds_read2_b64 v[164:167], v73 offset0:128 offset1:132
	v_pk_mul_f32 v[30:31], v[66:67], v[16:17] op_sel_hi:[1,0]
	s_nop 0
	s_waitcnt lgkmcnt(1)
	v_mfma_f32_16x16x32_f16 v[32:35], v[160:163], v[48:51], v[32:35]
	s_nop 0
	v_pk_mul_f32 v[28:29], v[64:65], v[16:17] op_sel_hi:[1,0]
	v_pk_mul_f32 v[22:23], v[74:75], v[16:17] op_sel_hi:[1,0]
	v_add_u32_e32 v74, 0xb000, v57
	ds_read2_b64 v[176:179], v74 offset0:160 offset1:164
	s_nop 0
	s_waitcnt lgkmcnt(1)
	v_mfma_f32_16x16x32_f16 v[52:55], v[164:167], v[48:51], v[28:31]
	s_nop 2
	s_nop 0
	v_pk_mul_f32 v[24:25], v[68:69], v[16:17] op_sel_hi:[1,0]
	v_add_u32_e32 v75, 0xb800, v57
	ds_read2_b64 v[140:143], v75 offset0:192 offset1:196
	v_mul_f32_e32 v92, v87, v16
	s_nop 0
	s_waitcnt lgkmcnt(1)
	v_mfma_f32_16x16x32_f16 v[58:61], v[176:179], v[48:51], v[24:27]
	s_nop 2
	s_nop 0
	v_pk_mul_f32 v[18:19], v[78:79], v[16:17] op_sel_hi:[1,0]
	v_pk_mul_f32 v[16:17], v[76:77], v[16:17] op_sel_hi:[1,0]
	v_add_u32_e32 v76, 0xc000, v57
	ds_read2_b64 v[180:183], v76 offset0:224 offset1:228
	ds_read2_b64 v[128:131], v72 offset0:104 offset1:108
	ds_read2_b64 v[132:135], v56 offset0:8 offset1:12
	ds_read2_b64 v[144:147], v70 offset0:40 offset1:44
	ds_read2_b64 v[148:151], v71 offset0:72 offset1:76
	ds_read2_b64 v[152:155], v76 offset0:232 offset1:236
	s_nop 0
	s_waitcnt lgkmcnt(6)
	v_mfma_f32_16x16x32_f16 v[62:65], v[140:143], v[48:51], v[20:23]
	s_nop 2
	s_nop 0
	s_nop 0
	v_cvt_pk_f16_f32 v69, v88, v90
	s_nop 0
	s_waitcnt lgkmcnt(5)
	v_mfma_f32_16x16x32_f16 v[48:51], v[180:183], v[48:51], v[16:19]
	s_nop 2
	s_nop 0
	v_cvt_pk_f16_f32 v68, v84, v86
	v_cvt_pk_f16_f32 v67, v80, v82
	v_cvt_pk_f16_f32 v66, v110, v112
	s_nop 0
	s_nop 0
	s_nop 0
	s_waitcnt lgkmcnt(3)
	v_mfma_f32_16x16x32_f16 v[16:19], v[132:135], v[66:69], v[44:47]
	s_nop 2
	s_nop 0
	v_mfma_f32_16x16x32_f16 v[28:31], v[128:131], v[66:69], v[32:35]
	s_nop 2
	ds_read2_b64 v[32:35], v73 offset0:136 offset1:140
	s_nop 0
	s_waitcnt lgkmcnt(3)
	v_mfma_f32_16x16x32_f16 v[20:23], v[144:147], v[66:69], v[40:43]
	s_nop 0
	s_waitcnt lgkmcnt(2)
	v_mfma_f32_16x16x32_f16 v[24:27], v[148:151], v[66:69], v[36:39]
	s_nop 0
	ds_read2_b64 v[40:43], v75 offset0:200 offset1:204
	s_nop 0
	ds_read2_b64 v[36:39], v74 offset0:168 offset1:172
	s_nop 0
	s_waitcnt lgkmcnt(3)
	v_mfma_f32_16x16x32_f16 v[44:47], v[152:155], v[66:69], v[48:51]
	s_nop 0
	s_waitcnt lgkmcnt(0)
	s_barrier
	ds_read_b128 v[128:131], v81 offset:17408
	ds_read_b128 v[132:135], v81 offset:17472
	ds_read_b128 v[136:139], v81 offset:17536
	ds_read_b128 v[140:143], v81 offset:21824
	ds_read_b128 v[144:147], v81 offset:17600
	ds_read_b128 v[148:151], v81 offset:26176
	ds_read_b128 v[152:155], v81 offset:21760
	ds_read_b128 v[156:159], v81 offset:21888
	ds_read_b128 v[160:163], v81 offset:21952
	ds_read_b128 v[164:167], v81 offset:26112
	ds_read_b128 v[176:179], v81 offset:26240
	ds_read_b128 v[180:183], v81 offset:26304
	s_nop 0
	s_nop 0
	v_mfma_f32_16x16x32_f16 v[32:35], v[32:35], v[66:69], v[52:55]
	s_nop 2
	s_nop 0
	s_waitcnt lgkmcnt(12)
	s_waitcnt lgkmcnt(11)
	v_mfma_f32_16x16x32_f16 v[48:51], v[128:131], v[12:15], 0
	ds_read_b128 v[128:131], v81 offset:30464
	s_nop 0
	s_waitcnt lgkmcnt(11)
	v_mfma_f32_16x16x32_f16 v[48:51], v[132:135], v[8:11], v[48:51]
	s_nop 0
	v_mfma_f32_16x16x32_f16 v[36:39], v[36:39], v[66:69], v[58:61]
	s_nop 2
	s_nop 0
	s_nop 0
	s_waitcnt lgkmcnt(10)
	v_mfma_f32_16x16x32_f16 v[48:51], v[136:139], v[4:7], v[48:51]
	s_nop 0
	v_mfma_f32_16x16x32_f16 v[40:43], v[40:43], v[66:69], v[62:65]
	s_nop 2
	s_nop 0
	s_nop 0
	s_waitcnt lgkmcnt(8)
	v_mfma_f32_16x16x32_f16 v[48:51], v[144:147], v[0:3], v[48:51]
	s_nop 0
	s_nop 0
	s_waitcnt lgkmcnt(6)
	v_mfma_f32_16x16x32_f16 v[52:55], v[152:155], v[12:15], 0
	v_mfma_f32_16x16x32_f16 v[52:55], v[140:143], v[8:11], v[52:55]
	s_nop 0
	s_nop 0
	s_waitcnt lgkmcnt(5)
	v_mfma_f32_16x16x32_f16 v[52:55], v[156:159], v[4:7], v[52:55]
	s_nop 0
	s_nop 0
	s_waitcnt lgkmcnt(4)
	v_mfma_f32_16x16x32_f16 v[52:55], v[160:163], v[0:3], v[52:55]
	s_nop 0
	s_nop 0
	s_waitcnt lgkmcnt(3)
	v_mfma_f32_16x16x32_f16 v[58:61], v[164:167], v[12:15], 0
	v_mfma_f32_16x16x32_f16 v[58:61], v[148:151], v[8:11], v[58:61]
	s_nop 0
	s_nop 0
	s_waitcnt lgkmcnt(2)
	v_mfma_f32_16x16x32_f16 v[58:61], v[176:179], v[4:7], v[58:61]
	s_nop 0
	s_nop 0
	s_waitcnt lgkmcnt(1)
	v_mfma_f32_16x16x32_f16 v[58:61], v[180:183], v[0:3], v[58:61]
	s_nop 0
	s_nop 0
	s_waitcnt lgkmcnt(0)
	v_mfma_f32_16x16x32_f16 v[12:15], v[128:131], v[12:15], 0
	ds_read_b128 v[62:65], v81 offset:30528
	s_nop 0
	s_waitcnt lgkmcnt(0)
	v_mfma_f32_16x16x32_f16 v[8:11], v[62:65], v[8:11], v[12:15]
	s_nop 4
	ds_read_b128 v[12:15], v81 offset:30592
	s_nop 0
	s_waitcnt lgkmcnt(0)
	v_mfma_f32_16x16x32_f16 v[4:7], v[12:15], v[4:7], v[8:11]
	s_nop 2
	ds_read_b128 v[8:11], v81 offset:30656
	v_mul_f32_e32 v12, 0x3db504f3, v58
	v_mul_f32_e32 v13, 0x3db504f3, v59
	s_nop 0
	s_waitcnt lgkmcnt(0)
	v_mfma_f32_16x16x32_f16 v[0:3], v[8:11], v[0:3], v[4:7]
	s_nop 2
	v_mul_f32_e32 v4, 0x3db504f3, v48
	v_mul_f32_e32 v5, 0x3db504f3, v49
	v_mul_f32_e32 v6, 0x3db504f3, v50
	v_mul_f32_e32 v7, 0x3db504f3, v51
	v_max3_f32 v4, v4, s4, v5
	v_mul_f32_e32 v8, 0x3db504f3, v52
	v_mul_f32_e32 v9, 0x3db504f3, v53
	v_max3_f32 v4, v4, v6, v7
	v_mul_f32_e32 v10, 0x3db504f3, v54
	v_mul_f32_e32 v11, 0x3db504f3, v55
	v_max3_f32 v4, v4, v8, v9
	v_max3_f32 v4, v4, v10, v11
	v_mul_f32_e32 v14, 0x3db504f3, v60
	v_mul_f32_e32 v15, 0x3db504f3, v61
	v_max3_f32 v4, v4, v12, v13
	v_mul_f32_e32 v56, 0x3db504f3, v0
	v_mul_f32_e32 v62, 0x3db504f3, v1
	v_max3_f32 v4, v4, v14, v15
	v_mul_f32_e32 v63, 0x3db504f3, v2
	v_mul_f32_e32 v64, 0x3db504f3, v3
	v_max3_f32 v4, v4, v56, v62
	v_max3_f32 v4, v4, v63, v64
	ds_bpermute_b32 v5, v117, v4
	s_nop 0
	s_waitcnt lgkmcnt(0)
	v_max_f32_e32 v5, v5, v5
	v_max_f32_e32 v4, v4, v5
	ds_bpermute_b32 v5, v119, v4
	s_nop 0
	s_waitcnt lgkmcnt(0)
	v_max3_f32 v6, v83, v4, v5
	v_fma_f32 v8, v52, s0, -v6
	v_mul_f32_e32 v8, 0x3fb8aa3b, v8
	v_exp_f32_e32 v107, v8
	v_fma_f32 v8, v53, s0, -v6
	v_mul_f32_e32 v8, 0x3fb8aa3b, v8
	v_exp_f32_e32 v109, v8
	v_fma_f32 v8, v54, s0, -v6
	v_mul_f32_e32 v8, 0x3fb8aa3b, v8
	v_exp_f32_e32 v111, v8
	v_fma_f32 v8, v55, s0, -v6
	v_mul_f32_e32 v8, 0x3fb8aa3b, v8
	v_sub_f32_e32 v4, v83, v6
	v_exp_f32_e32 v113, v8
	v_fma_f32 v8, v58, s0, -v6
	v_mul_f32_e32 v7, 0x3fb8aa3b, v4
	v_fma_f32 v4, v48, s0, -v6
	v_mul_f32_e32 v8, 0x3fb8aa3b, v8
	v_fma_f32 v0, v0, s0, -v6
	v_mul_f32_e32 v4, 0x3fb8aa3b, v4
	v_exp_f32_e32 v81, v8
	v_fma_f32 v8, v59, s0, -v6
	v_mul_f32_e32 v0, 0x3fb8aa3b, v0
	v_exp_f32_e32 v95, v4
	v_fma_f32 v4, v49, s0, -v6
	v_mul_f32_e32 v8, 0x3fb8aa3b, v8
	v_exp_f32_e32 v89, v0
	v_fma_f32 v0, v1, s0, -v6
	v_exp_f32_e32 v56, v7
	v_mul_f32_e32 v4, 0x3fb8aa3b, v4
	v_exp_f32_e32 v83, v8
	v_fma_f32 v8, v60, s0, -v6
	v_mul_f32_e32 v0, 0x3fb8aa3b, v0
	v_exp_f32_e32 v97, v4
	v_fma_f32 v4, v50, s0, -v6
	v_mul_f32_e32 v8, 0x3fb8aa3b, v8
	v_exp_f32_e32 v91, v0
	v_fma_f32 v0, v2, s0, -v6
	v_mul_f32_e32 v4, 0x3fb8aa3b, v4
	v_exp_f32_e32 v85, v8
	v_fma_f32 v8, v61, s0, -v6
	v_mul_f32_e32 v0, 0x3fb8aa3b, v0
	v_exp_f32_e32 v99, v4
	v_fma_f32 v4, v51, s0, -v6
	v_mul_f32_e32 v8, 0x3fb8aa3b, v8
	v_exp_f32_e32 v93, v0
	v_fma_f32 v0, v3, s0, -v6
	v_pk_mul_f32 v[6:7], v[42:43], v[56:57] op_sel_hi:[1,0]
	v_add_u32_e32 v42, 0xe000, v57
	ds_read2_b64 v[132:135], v42 offset0:64 offset1:68
	v_exp_f32_e32 v87, v8
	v_pk_mul_f32 v[10:11], v[38:39], v[56:57] op_sel_hi:[1,0]
	v_pk_mul_f32 v[8:9], v[36:37], v[56:57] op_sel_hi:[1,0]
	s_nop 0
	v_mul_f32_e32 v4, 0x3fb8aa3b, v4
	v_exp_f32_e32 v105, v4
	v_pk_add_f32 v[4:5], v[94:95], v[168:169]
	v_mul_f32_e32 v0, 0x3fb8aa3b, v0
	v_pk_add_f32 v[4:5], v[96:97], v[4:5]
	v_exp_f32_e32 v60, v0
	v_pk_add_f32 v[4:5], v[98:99], v[4:5]
	v_pk_mul_f32 v[50:51], v[22:23], v[56:57] op_sel_hi:[1,0]
	v_pk_add_f32 v[4:5], v[104:105], v[4:5]
	v_pk_mul_f32 v[48:49], v[20:21], v[56:57] op_sel_hi:[1,0]
	v_pk_add_f32 v[0:1], v[106:107], v[4:5]
	v_pk_mul_f32 v[22:23], v[26:27], v[56:57] op_sel_hi:[1,0]
	v_pk_add_f32 v[0:1], v[108:109], v[0:1]
	v_pk_mul_f32 v[20:21], v[24:25], v[56:57] op_sel_hi:[1,0]
	v_cvt_pk_f16_f32 v27, v111, v113
	v_cvt_pk_f16_f32 v26, v107, v109
	v_cvt_pk_f16_f32 v25, v99, v105
	v_cvt_pk_f16_f32 v24, v95, v97
	v_add_u32_e32 v43, 0xe800, v57
	ds_read2_b64 v[136:139], v43 offset0:96 offset1:100
	v_pk_add_f32 v[0:1], v[110:111], v[0:1]
	s_nop 0
	s_waitcnt lgkmcnt(1)
	v_mfma_f32_16x16x32_f16 v[20:23], v[132:135], v[24:27], v[20:23]
	s_nop 0
	v_pk_add_f32 v[0:1], v[112:113], v[0:1]
	v_pk_mul_f32 v[54:55], v[18:19], v[56:57] op_sel_hi:[1,0]
	v_pk_add_f32 v[0:1], v[80:81], v[0:1]
	v_pk_mul_f32 v[52:53], v[16:17], v[56:57] op_sel_hi:[1,0]
	v_pk_add_f32 v[0:1], v[82:83], v[0:1]
	v_pk_mul_f32 v[18:19], v[30:31], v[56:57] op_sel_hi:[1,0]
	v_pk_add_f32 v[0:1], v[84:85], v[0:1]
	v_pk_mul_f32 v[16:17], v[28:29], v[56:57] op_sel_hi:[1,0]
	v_pk_add_f32 v[0:1], v[86:87], v[0:1]
	v_pk_mul_f32 v[14:15], v[34:35], v[56:57] op_sel_hi:[1,0]
	v_pk_add_f32 v[0:1], v[88:89], v[0:1]
	s_nop 0
	s_waitcnt lgkmcnt(0)
	v_mfma_f32_16x16x32_f16 v[16:19], v[136:139], v[24:27], v[16:19]
	v_add_f32_e64 v0, v90, v0
	v_add_f32_e64 v1, v91, v1
	v_pk_mul_f32 v[12:13], v[32:33], v[56:57] op_sel_hi:[1,0]
	v_pk_add_f32 v[58:59], v[92:93], v[0:1]
	v_pk_mul_f32 v[0:1], v[44:45], v[56:57] op_sel_hi:[1,0]
	v_add_u32_e32 v44, 0xf000, v57
	ds_read2_b64 v[144:147], v44 offset0:128 offset1:132
	s_nop 0
	v_add_u32_e32 v45, 0xf800, v57
	ds_read2_b64 v[152:155], v45 offset0:160 offset1:164
	s_nop 0
	s_waitcnt lgkmcnt(1)
	v_mfma_f32_16x16x32_f16 v[12:15], v[144:147], v[24:27], v[12:15]
	s_nop 0
	v_pk_mul_f32 v[4:5], v[40:41], v[56:57] op_sel_hi:[1,0]
	v_add_u32_e32 v40, 0xd000, v57
	v_pk_mul_f32 v[2:3], v[46:47], v[56:57] op_sel_hi:[1,0]
	v_add_u32_e32 v46, 0x3000, v40
	ds_read2_b64 v[140:143], v46 offset0:192 offset1:196
	ds_read2_b64 v[156:159], v40 offset1:4
	s_nop 0
	s_waitcnt lgkmcnt(2)
	v_mfma_f32_16x16x32_f16 v[8:11], v[152:155], v[24:27], v[8:11]
	s_nop 0
	v_add_u32_e32 v41, 0xd800, v57
	ds_read2_b64 v[160:163], v41 offset0:32 offset1:36
	ds_read2_b64 v[164:167], v40 offset0:8 offset1:12
	ds_read2_b64 v[148:151], v41 offset0:40 offset1:44
	ds_read2_b64 v[176:179], v42 offset0:72 offset1:76
	ds_read2_b64 v[180:183], v43 offset0:104 offset1:108
	ds_read2_b64 v[128:131], v44 offset0:136 offset1:140
	ds_read2_b64 v[132:135], v45 offset0:168 offset1:172
	ds_read2_b64 v[136:139], v46 offset0:200 offset1:204
	v_add_u32_e32 v47, 0x3800, v40
	s_nop 0
	s_nop 0
	s_nop 0
	s_waitcnt lgkmcnt(9)
	v_mfma_f32_16x16x32_f16 v[4:7], v[140:143], v[24:27], v[4:7]
	ds_read2_b64 v[36:39], v47 offset0:224 offset1:228
	v_readlane_b32 s0, v255, 59
	s_lshl_b32 s0, s0, 1
	s_nop 0
	s_waitcnt lgkmcnt(9)
	v_mfma_f32_16x16x32_f16 v[28:31], v[156:159], v[24:27], v[52:55]
	v_lshlrev_b32_e32 v168, 1, v115
	s_nop 0
	s_waitcnt lgkmcnt(8)
	v_mfma_f32_16x16x32_f16 v[32:35], v[160:163], v[24:27], v[48:51]
	s_nop 0
	s_waitcnt lgkmcnt(0)
	v_mfma_f32_16x16x32_f16 v[0:3], v[36:39], v[24:27], v[0:3]
	s_nop 0
	v_cvt_pk_f16_f32 v39, v93, v60
	v_cvt_pk_f16_f32 v38, v89, v91
	v_cvt_pk_f16_f32 v37, v85, v87
	v_cvt_pk_f16_f32 v36, v81, v83
	s_nop 0
	s_nop 0
	v_mfma_f32_16x16x32_f16 v[28:31], v[164:167], v[36:39], v[28:31]
	s_nop 0
	s_nop 0
	v_mfma_f32_16x16x32_f16 v[24:27], v[148:151], v[36:39], v[32:35]
	s_nop 2
	s_nop 0
	s_nop 0
	v_mfma_f32_16x16x32_f16 v[20:23], v[176:179], v[36:39], v[20:23]
	s_nop 0
	s_nop 0
	v_mfma_f32_16x16x32_f16 v[16:19], v[180:183], v[36:39], v[16:19]
	s_nop 0
	s_nop 0
	v_mfma_f32_16x16x32_f16 v[12:15], v[128:131], v[36:39], v[12:15]
	s_nop 0
	s_nop 0
	v_mfma_f32_16x16x32_f16 v[8:11], v[132:135], v[36:39], v[8:11]
	s_nop 0
	s_nop 0
	v_mfma_f32_16x16x32_f16 v[4:7], v[136:139], v[36:39], v[4:7]
	ds_read2_b64 v[32:35], v47 offset0:232 offset1:236
	s_nop 0
	s_waitcnt lgkmcnt(0)
	s_barrier
	v_mfma_f32_16x16x32_f16 v[0:3], v[32:35], v[36:39], v[0:3]
	v_add_f32_e32 v32, v59, v60
	v_fmac_f32_e32 v32, v58, v56
	ds_bpermute_b32 v33, v117, v32
	s_waitcnt lgkmcnt(0)
	v_add_f32_e32 v32, v32, v33
	ds_bpermute_b32 v33, v119, v32
	s_waitcnt lgkmcnt(0)
	v_add_f32_e32 v32, v32, v33
	v_div_scale_f32 v33, s[4:5], v32, v32, 1.0
	v_rcp_f32_e32 v34, v33
	s_mov_b64 s[4:5], 0x2c20
	v_fma_f32 v35, -v33, v34, 1.0
	v_fmac_f32_e32 v34, v35, v34
	v_div_scale_f32 v35, vcc, 1.0, v32, 1.0
	v_mul_f32_e32 v36, v35, v34
	v_fma_f32 v37, -v33, v36, v35
	v_fmac_f32_e32 v36, v37, v34
	v_fma_f32 v33, -v33, v36, v35
	v_div_fmas_f32 v33, v33, v34, v36
	v_lshl_add_u64 v[34:35], v[102:103], 0, s[0:1]
	v_lshl_add_u64 v[38:39], v[34:35], 0, v[168:169]
	v_lshl_add_u64 v[34:35], v[38:39], 0, s[4:5]
	v_add_co_u32_e32 v38, vcc, s33, v38
	v_div_fixup_f32 v32, v33, v32, 1.0
	s_nop 0
	v_addc_co_u32_e32 v39, vcc, 0, v39, vcc
	global_load_dwordx2 v[38:39], v[38:39], off offset:3104
	v_lshlrev_b64 v[36:37], 12, v[100:101]
	v_lshl_add_u64 v[36:37], s[20:21], 0, v[36:37]
	v_lshl_add_u64 v[36:37], v[36:37], 0, s[0:1]
	s_mov_b32 s0, 0x4800000
	s_waitcnt vmcnt(0)
	v_cvt_f32_f16_sdwa v33, v38 dst_sel:DWORD dst_unused:UNUSED_PAD src0_sel:WORD_1
	v_cvt_f32_f16_e32 v38, v38
	v_mul_f32_e32 v41, 0xbfb8aa3b, v33
	v_mul_f32_e32 v40, 0xbfb8aa3b, v38
	v_exp_f32_e32 v40, v40
	v_exp_f32_e32 v41, v41
	v_pk_mul_f32 v[28:29], v[28:29], v[32:33] op_sel_hi:[1,0]
	v_pk_add_f32 v[40:41], v[40:41], 1.0 op_sel_hi:[1,0]
	s_nop 0
	v_div_scale_f32 v42, s[4:5], v41, v41, v33
	v_rcp_f32_e32 v43, v42
	s_nop 0
	v_fma_f32 v44, -v42, v43, 1.0
	v_fmac_f32_e32 v43, v44, v43
	v_div_scale_f32 v44, vcc, v33, v41, v33
	v_mul_f32_e32 v45, v44, v43
	v_fma_f32 v46, -v42, v45, v44
	v_fmac_f32_e32 v45, v46, v43
	v_fma_f32 v42, -v42, v45, v44
	v_div_fmas_f32 v42, v42, v43, v45
	v_div_fixup_f32 v41, v42, v41, v33
	v_div_scale_f32 v33, s[4:5], v40, v40, v38
	v_rcp_f32_e32 v42, v33
	s_nop 0
	v_fma_f32 v43, -v33, v42, 1.0
	v_fmac_f32_e32 v42, v43, v42
	v_div_scale_f32 v43, vcc, v38, v40, v38
	v_mul_f32_e32 v44, v43, v42
	v_fma_f32 v45, -v33, v44, v43
	v_fmac_f32_e32 v44, v45, v42
	v_fma_f32 v33, -v33, v44, v43
	v_div_fmas_f32 v33, v33, v42, v44
	v_div_fixup_f32 v40, v33, v40, v38
	v_cvt_f32_f16_sdwa v33, v39 dst_sel:DWORD dst_unused:UNUSED_PAD src0_sel:WORD_1
	v_cvt_f32_f16_e32 v39, v39
	v_pk_mul_f32 v[28:29], v[28:29], v[40:41]
	v_pk_mul_f32 v[30:31], v[30:31], v[32:33] op_sel_hi:[1,0]
	v_cvt_pk_f16_f32 v38, v28, v29
	v_mul_f32_e32 v28, 0xbfb8aa3b, v39
	v_mul_f32_e32 v29, 0xbfb8aa3b, v33
	v_exp_f32_e32 v28, v28
	v_exp_f32_e32 v29, v29
	s_nop 0
	v_pk_add_f32 v[28:29], v[28:29], 1.0 op_sel_hi:[1,0]
	s_nop 0
	v_div_scale_f32 v40, s[4:5], v29, v29, v33
	v_rcp_f32_e32 v41, v40
	s_nop 0
	v_fma_f32 v42, -v40, v41, 1.0
	v_fmac_f32_e32 v41, v42, v41
	v_div_scale_f32 v42, vcc, v33, v29, v33
	v_mul_f32_e32 v43, v42, v41
	v_fma_f32 v44, -v40, v43, v42
	v_fmac_f32_e32 v43, v44, v41
	v_fma_f32 v40, -v40, v43, v42
	v_div_fmas_f32 v40, v40, v41, v43
	v_div_fixup_f32 v29, v40, v29, v33
	v_div_scale_f32 v33, s[4:5], v28, v28, v39
	v_rcp_f32_e32 v40, v33
	s_mov_b64 s[4:5], 0x4800300
	v_fma_f32 v41, -v33, v40, 1.0
	v_fmac_f32_e32 v40, v41, v40
	v_div_scale_f32 v41, vcc, v39, v28, v39
	v_mul_f32_e32 v42, v41, v40
	v_fma_f32 v43, -v33, v42, v41
	v_fmac_f32_e32 v42, v43, v40
	v_fma_f32 v33, -v33, v42, v41
	v_div_fmas_f32 v33, v33, v40, v42
	v_div_fixup_f32 v28, v33, v28, v39
	v_pk_mul_f32 v[28:29], v[30:31], v[28:29]
	v_lshl_add_u64 v[30:31], v[36:37], 0, v[168:169]
	v_cvt_pk_f16_f32 v39, v28, v29
	v_lshl_add_u64 v[28:29], v[30:31], 0, s[4:5]
	v_add_co_u32_e32 v30, vcc, s0, v30
	s_nop 1
	v_addc_co_u32_e32 v31, vcc, 0, v31, vcc
	global_load_dwordx2 v[60:61], v[34:35], off offset:32
	global_load_dwordx2 v[62:63], v[34:35], off offset:64
	global_load_dwordx2 v[64:65], v[34:35], off offset:96
	global_load_dwordx2 v[66:67], v[34:35], off offset:128
	global_load_dwordx2 v[68:69], v[34:35], off offset:160
	global_load_dwordx2 v[70:71], v[34:35], off offset:192
	global_load_dwordx2 v[72:73], v[34:35], off offset:224
	global_store_dwordx2 v[30:31], v[38:39], off offset:768
	s_waitcnt vmcnt(7)
	v_cvt_f32_f16_sdwa v33, v60 dst_sel:DWORD dst_unused:UNUSED_PAD src0_sel:WORD_1
	v_cvt_f32_f16_e32 v30, v60
	v_mul_f32_e32 v37, 0xbfb8aa3b, v33
	v_mul_f32_e32 v36, 0xbfb8aa3b, v30
	v_exp_f32_e32 v36, v36
	v_exp_f32_e32 v37, v37
	v_pk_mul_f32 v[24:25], v[24:25], v[32:33] op_sel_hi:[1,0]
	v_pk_add_f32 v[36:37], v[36:37], 1.0 op_sel_hi:[1,0]
	s_nop 0
	v_div_scale_f32 v38, s[4:5], v37, v37, v33
	v_rcp_f32_e32 v39, v38
	s_nop 0
	v_fma_f32 v40, -v38, v39, 1.0
	v_fmac_f32_e32 v39, v40, v39
	v_div_scale_f32 v40, vcc, v33, v37, v33
	v_mul_f32_e32 v41, v40, v39
	v_fma_f32 v42, -v38, v41, v40
	v_fmac_f32_e32 v41, v42, v39
	v_fma_f32 v38, -v38, v41, v40
	v_div_fmas_f32 v38, v38, v39, v41
	v_div_fixup_f32 v37, v38, v37, v33
	v_div_scale_f32 v33, s[4:5], v36, v36, v30
	v_rcp_f32_e32 v38, v33
	s_nop 0
	v_fma_f32 v39, -v33, v38, 1.0
	v_fmac_f32_e32 v38, v39, v38
	v_div_scale_f32 v39, vcc, v30, v36, v30
	v_mul_f32_e32 v40, v39, v38
	v_fma_f32 v41, -v33, v40, v39
	v_fmac_f32_e32 v40, v41, v38
	v_fma_f32 v33, -v33, v40, v39
	v_div_fmas_f32 v33, v33, v38, v40
	v_div_fixup_f32 v36, v33, v36, v30
	v_pk_mul_f32 v[24:25], v[24:25], v[36:37]
	v_cvt_f32_f16_e32 v33, v61
	v_cvt_pk_f16_f32 v24, v24, v25
	v_cvt_f32_f16_sdwa v25, v61 dst_sel:DWORD dst_unused:UNUSED_PAD src0_sel:WORD_1
	v_mul_f32_e32 v30, 0xbfb8aa3b, v33
	v_exp_f32_e32 v30, v30
	v_mul_f32_e32 v31, 0xbfb8aa3b, v25
	v_exp_f32_e32 v31, v31
	v_pk_mul_f32 v[26:27], v[26:27], v[32:33] op_sel_hi:[1,0]
	v_pk_mul_f32 v[20:21], v[20:21], v[32:33] op_sel_hi:[1,0]
	v_pk_add_f32 v[30:31], v[30:31], 1.0 op_sel_hi:[1,0]
	s_nop 0
	v_div_scale_f32 v36, s[4:5], v31, v31, v25
	v_rcp_f32_e32 v37, v36
	s_nop 0
	v_fma_f32 v38, -v36, v37, 1.0
	v_fmac_f32_e32 v37, v38, v37
	v_div_scale_f32 v38, vcc, v25, v31, v25
	v_mul_f32_e32 v39, v38, v37
	v_fma_f32 v40, -v36, v39, v38
	v_fmac_f32_e32 v39, v40, v37
	v_fma_f32 v36, -v36, v39, v38
	v_div_fmas_f32 v36, v36, v37, v39
	v_div_fixup_f32 v31, v36, v31, v25
	v_div_scale_f32 v25, s[4:5], v30, v30, v33
	v_rcp_f32_e32 v36, v25
	s_nop 0
	v_fma_f32 v37, -v25, v36, 1.0
	v_fmac_f32_e32 v36, v37, v36
	v_div_scale_f32 v37, vcc, v33, v30, v33
	v_mul_f32_e32 v38, v37, v36
	v_fma_f32 v39, -v25, v38, v37
	v_fmac_f32_e32 v38, v39, v36
	v_fma_f32 v25, -v25, v38, v37
	v_div_fmas_f32 v25, v25, v36, v38
	v_div_fixup_f32 v30, v25, v30, v33
	v_pk_mul_f32 v[26:27], v[26:27], v[30:31]
	s_nop 0
	v_cvt_pk_f16_f32 v25, v26, v27
	global_store_dwordx2 v[28:29], v[24:25], off offset:32
	s_waitcnt vmcnt(7)
	v_cvt_f32_f16_sdwa v30, v62 dst_sel:DWORD dst_unused:UNUSED_PAD src0_sel:WORD_1
	v_cvt_f32_f16_e32 v24, v62
	v_mul_f32_e32 v27, 0xbfb8aa3b, v30
	v_mul_f32_e32 v26, 0xbfb8aa3b, v24
	v_exp_f32_e32 v26, v26
	v_exp_f32_e32 v27, v27
	s_nop 0
	v_pk_add_f32 v[26:27], v[26:27], 1.0 op_sel_hi:[1,0]
	s_nop 0
	v_div_scale_f32 v31, s[4:5], v27, v27, v30
	v_rcp_f32_e32 v33, v31
	s_nop 0
	v_fma_f32 v36, -v31, v33, 1.0
	v_fmac_f32_e32 v33, v36, v33
	v_div_scale_f32 v36, vcc, v30, v27, v30
	v_mul_f32_e32 v37, v36, v33
	v_fma_f32 v38, -v31, v37, v36
	v_fmac_f32_e32 v37, v38, v33
	v_fma_f32 v31, -v31, v37, v36
	v_div_fmas_f32 v31, v31, v33, v37
	v_div_fixup_f32 v27, v31, v27, v30
	v_div_scale_f32 v30, s[4:5], v26, v26, v24
	v_rcp_f32_e32 v31, v30
	s_nop 0
	v_fma_f32 v33, -v30, v31, 1.0
	v_fmac_f32_e32 v31, v33, v31
	v_div_scale_f32 v33, vcc, v24, v26, v24
	v_mul_f32_e32 v36, v33, v31
	v_fma_f32 v37, -v30, v36, v33
	v_fmac_f32_e32 v36, v37, v31
	v_fma_f32 v30, -v30, v36, v33
	v_div_fmas_f32 v30, v30, v31, v36
	v_div_fixup_f32 v26, v30, v26, v24
	v_pk_mul_f32 v[20:21], v[20:21], v[26:27]
	v_cvt_f32_f16_e32 v26, v63
	v_cvt_pk_f16_f32 v20, v20, v21
	v_cvt_f32_f16_sdwa v21, v63 dst_sel:DWORD dst_unused:UNUSED_PAD src0_sel:WORD_1
	v_pk_mul_f32 v[22:23], v[22:23], v[32:33] op_sel_hi:[1,0]
	v_mul_f32_e32 v24, 0xbfb8aa3b, v26
	v_exp_f32_e32 v24, v24
	v_mul_f32_e32 v25, 0xbfb8aa3b, v21
	v_exp_f32_e32 v25, v25
	s_nop 0
	v_pk_add_f32 v[24:25], v[24:25], 1.0 op_sel_hi:[1,0]
	s_nop 0
	v_div_scale_f32 v27, s[4:5], v25, v25, v21
	v_rcp_f32_e32 v30, v27
	s_nop 0
	v_fma_f32 v31, -v27, v30, 1.0
	v_fmac_f32_e32 v30, v31, v30
	v_div_scale_f32 v31, vcc, v21, v25, v21
	v_mul_f32_e32 v33, v31, v30
	v_fma_f32 v36, -v27, v33, v31
	v_fmac_f32_e32 v33, v36, v30
	v_fma_f32 v27, -v27, v33, v31
	v_div_fmas_f32 v27, v27, v30, v33
	v_div_fixup_f32 v25, v27, v25, v21
	v_div_scale_f32 v21, s[4:5], v24, v24, v26
	v_rcp_f32_e32 v27, v21
	s_nop 0
	v_fma_f32 v30, -v21, v27, 1.0
	v_fmac_f32_e32 v27, v30, v27
	v_div_scale_f32 v30, vcc, v26, v24, v26
	v_mul_f32_e32 v31, v30, v27
	v_fma_f32 v33, -v21, v31, v30
	v_fmac_f32_e32 v31, v33, v27
	v_fma_f32 v21, -v21, v31, v30
	v_div_fmas_f32 v21, v21, v27, v31
	v_div_fixup_f32 v24, v21, v24, v26
	v_pk_mul_f32 v[22:23], v[22:23], v[24:25]
	v_pk_mul_f32 v[16:17], v[16:17], v[32:33] op_sel_hi:[1,0]
	v_cvt_pk_f16_f32 v21, v22, v23
	global_store_dwordx2 v[28:29], v[20:21], off offset:64
	v_pk_mul_f32 v[18:19], v[18:19], v[32:33] op_sel_hi:[1,0]
	v_pk_mul_f32 v[12:13], v[12:13], v[32:33] op_sel_hi:[1,0]
	v_pk_mul_f32 v[14:15], v[14:15], v[32:33] op_sel_hi:[1,0]
	v_pk_mul_f32 v[8:9], v[8:9], v[32:33] op_sel_hi:[1,0]
	v_pk_mul_f32 v[10:11], v[10:11], v[32:33] op_sel_hi:[1,0]
	v_pk_mul_f32 v[4:5], v[4:5], v[32:33] op_sel_hi:[1,0]
	v_pk_mul_f32 v[6:7], v[6:7], v[32:33] op_sel_hi:[1,0]
	v_pk_mul_f32 v[0:1], v[0:1], v[32:33] op_sel_hi:[1,0]
	v_pk_mul_f32 v[2:3], v[2:3], v[32:33] op_sel_hi:[1,0]
	s_waitcnt vmcnt(7)
	v_cvt_f32_f16_sdwa v24, v64 dst_sel:DWORD dst_unused:UNUSED_PAD src0_sel:WORD_1
	v_cvt_f32_f16_e32 v20, v64
	v_mul_f32_e32 v23, 0xbfb8aa3b, v24
	v_mul_f32_e32 v22, 0xbfb8aa3b, v20
	v_exp_f32_e32 v22, v22
	v_exp_f32_e32 v23, v23
	s_nop 0
	v_pk_add_f32 v[22:23], v[22:23], 1.0 op_sel_hi:[1,0]
	s_nop 0
	v_div_scale_f32 v25, s[4:5], v23, v23, v24
	v_rcp_f32_e32 v26, v25
	s_nop 0
	v_fma_f32 v27, -v25, v26, 1.0
	v_fmac_f32_e32 v26, v27, v26
	v_div_scale_f32 v27, vcc, v24, v23, v24
	v_mul_f32_e32 v30, v27, v26
	v_fma_f32 v31, -v25, v30, v27
	v_fmac_f32_e32 v30, v31, v26
	v_fma_f32 v25, -v25, v30, v27
	v_div_fmas_f32 v25, v25, v26, v30
	v_div_fixup_f32 v23, v25, v23, v24
	v_div_scale_f32 v24, s[4:5], v22, v22, v20
	v_rcp_f32_e32 v25, v24
	s_nop 0
	v_fma_f32 v26, -v24, v25, 1.0
	v_fmac_f32_e32 v25, v26, v25
	v_div_scale_f32 v26, vcc, v20, v22, v20
	v_mul_f32_e32 v27, v26, v25
	v_fma_f32 v30, -v24, v27, v26
	v_fmac_f32_e32 v27, v30, v25
	v_fma_f32 v24, -v24, v27, v26
	v_div_fmas_f32 v24, v24, v25, v27
	v_div_fixup_f32 v22, v24, v22, v20
	v_pk_mul_f32 v[16:17], v[16:17], v[22:23]
	v_cvt_f32_f16_e32 v22, v65
	v_cvt_pk_f16_f32 v16, v16, v17
	v_cvt_f32_f16_sdwa v17, v65 dst_sel:DWORD dst_unused:UNUSED_PAD src0_sel:WORD_1
	v_mul_f32_e32 v20, 0xbfb8aa3b, v22
	v_exp_f32_e32 v20, v20
	v_mul_f32_e32 v21, 0xbfb8aa3b, v17
	v_exp_f32_e32 v21, v21
	s_nop 0
	v_pk_add_f32 v[20:21], v[20:21], 1.0 op_sel_hi:[1,0]
	s_nop 0
	v_div_scale_f32 v23, s[4:5], v21, v21, v17
	v_rcp_f32_e32 v24, v23
	s_nop 0
	v_fma_f32 v25, -v23, v24, 1.0
	v_fmac_f32_e32 v24, v25, v24
	v_div_scale_f32 v25, vcc, v17, v21, v17
	v_mul_f32_e32 v26, v25, v24
	v_fma_f32 v27, -v23, v26, v25
	v_fmac_f32_e32 v26, v27, v24
	v_fma_f32 v23, -v23, v26, v25
	v_div_fmas_f32 v23, v23, v24, v26
	v_div_fixup_f32 v21, v23, v21, v17
	v_div_scale_f32 v17, s[4:5], v20, v20, v22
	v_rcp_f32_e32 v23, v17
	s_nop 0
	v_fma_f32 v24, -v17, v23, 1.0
	v_fmac_f32_e32 v23, v24, v23
	v_div_scale_f32 v24, vcc, v22, v20, v22
	v_mul_f32_e32 v25, v24, v23
	v_fma_f32 v26, -v17, v25, v24
	v_fmac_f32_e32 v25, v26, v23
	v_fma_f32 v17, -v17, v25, v24
	v_div_fmas_f32 v17, v17, v23, v25
	v_div_fixup_f32 v20, v17, v20, v22
	v_pk_mul_f32 v[18:19], v[18:19], v[20:21]
	s_nop 0
	v_cvt_pk_f16_f32 v17, v18, v19
	global_store_dwordx2 v[28:29], v[16:17], off offset:96
	s_waitcnt vmcnt(7)
	v_cvt_f32_f16_sdwa v20, v66 dst_sel:DWORD dst_unused:UNUSED_PAD src0_sel:WORD_1
	v_cvt_f32_f16_e32 v16, v66
	v_mul_f32_e32 v19, 0xbfb8aa3b, v20
	v_mul_f32_e32 v18, 0xbfb8aa3b, v16
	v_exp_f32_e32 v18, v18
	v_exp_f32_e32 v19, v19
	s_nop 0
	v_pk_add_f32 v[18:19], v[18:19], 1.0 op_sel_hi:[1,0]
	s_nop 0
	v_div_scale_f32 v21, s[4:5], v19, v19, v20
	v_rcp_f32_e32 v22, v21
	s_nop 0
	v_fma_f32 v23, -v21, v22, 1.0
	v_fmac_f32_e32 v22, v23, v22
	v_div_scale_f32 v23, vcc, v20, v19, v20
	v_mul_f32_e32 v24, v23, v22
	v_fma_f32 v25, -v21, v24, v23
	v_fmac_f32_e32 v24, v25, v22
	v_fma_f32 v21, -v21, v24, v23
	v_div_fmas_f32 v21, v21, v22, v24
	v_div_fixup_f32 v19, v21, v19, v20
	v_div_scale_f32 v20, s[4:5], v18, v18, v16
	v_rcp_f32_e32 v21, v20
	s_nop 0
	v_fma_f32 v22, -v20, v21, 1.0
	v_fmac_f32_e32 v21, v22, v21
	v_div_scale_f32 v22, vcc, v16, v18, v16
	v_mul_f32_e32 v23, v22, v21
	v_fma_f32 v24, -v20, v23, v22
	v_fmac_f32_e32 v23, v24, v21
	v_fma_f32 v20, -v20, v23, v22
	v_div_fmas_f32 v20, v20, v21, v23
	v_div_fixup_f32 v18, v20, v18, v16
	v_pk_mul_f32 v[12:13], v[12:13], v[18:19]
	v_cvt_f32_f16_e32 v18, v67
	v_cvt_pk_f16_f32 v12, v12, v13
	v_cvt_f32_f16_sdwa v13, v67 dst_sel:DWORD dst_unused:UNUSED_PAD src0_sel:WORD_1
	v_mul_f32_e32 v16, 0xbfb8aa3b, v18
	v_exp_f32_e32 v16, v16
	v_mul_f32_e32 v17, 0xbfb8aa3b, v13
	v_exp_f32_e32 v17, v17
	s_nop 0
	v_pk_add_f32 v[16:17], v[16:17], 1.0 op_sel_hi:[1,0]
	s_nop 0
	v_div_scale_f32 v19, s[4:5], v17, v17, v13
	v_rcp_f32_e32 v20, v19
	s_nop 0
	v_fma_f32 v21, -v19, v20, 1.0
	v_fmac_f32_e32 v20, v21, v20
	v_div_scale_f32 v21, vcc, v13, v17, v13
	v_mul_f32_e32 v22, v21, v20
	v_fma_f32 v23, -v19, v22, v21
	v_fmac_f32_e32 v22, v23, v20
	v_fma_f32 v19, -v19, v22, v21
	v_div_fmas_f32 v19, v19, v20, v22
	v_div_fixup_f32 v17, v19, v17, v13
	v_div_scale_f32 v13, s[4:5], v16, v16, v18
	v_rcp_f32_e32 v19, v13
	s_nop 0
	v_fma_f32 v20, -v13, v19, 1.0
	v_fmac_f32_e32 v19, v20, v19
	v_div_scale_f32 v20, vcc, v18, v16, v18
	v_mul_f32_e32 v21, v20, v19
	v_fma_f32 v22, -v13, v21, v20
	v_fmac_f32_e32 v21, v22, v19
	v_fma_f32 v13, -v13, v21, v20
	v_div_fmas_f32 v13, v13, v19, v21
	v_div_fixup_f32 v16, v13, v16, v18
	v_pk_mul_f32 v[14:15], v[14:15], v[16:17]
	s_nop 0
	v_cvt_pk_f16_f32 v13, v14, v15
	global_store_dwordx2 v[28:29], v[12:13], off offset:128
	s_waitcnt vmcnt(7)
	v_cvt_f32_f16_sdwa v16, v68 dst_sel:DWORD dst_unused:UNUSED_PAD src0_sel:WORD_1
	v_cvt_f32_f16_e32 v12, v68
	v_mul_f32_e32 v15, 0xbfb8aa3b, v16
	v_mul_f32_e32 v14, 0xbfb8aa3b, v12
	v_exp_f32_e32 v14, v14
	v_exp_f32_e32 v15, v15
	s_nop 0
	v_pk_add_f32 v[14:15], v[14:15], 1.0 op_sel_hi:[1,0]
	s_nop 0
	v_div_scale_f32 v17, s[4:5], v15, v15, v16
	v_rcp_f32_e32 v18, v17
	s_nop 0
	v_fma_f32 v19, -v17, v18, 1.0
	v_fmac_f32_e32 v18, v19, v18
	v_div_scale_f32 v19, vcc, v16, v15, v16
	v_mul_f32_e32 v20, v19, v18
	v_fma_f32 v21, -v17, v20, v19
	v_fmac_f32_e32 v20, v21, v18
	v_fma_f32 v17, -v17, v20, v19
	v_div_fmas_f32 v17, v17, v18, v20
	v_div_fixup_f32 v15, v17, v15, v16
	v_div_scale_f32 v16, s[4:5], v14, v14, v12
	v_rcp_f32_e32 v17, v16
	s_nop 0
	v_fma_f32 v18, -v16, v17, 1.0
	v_fmac_f32_e32 v17, v18, v17
	v_div_scale_f32 v18, vcc, v12, v14, v12
	v_mul_f32_e32 v19, v18, v17
	v_fma_f32 v20, -v16, v19, v18
	v_fmac_f32_e32 v19, v20, v17
	v_fma_f32 v16, -v16, v19, v18
	v_div_fmas_f32 v16, v16, v17, v19
	v_div_fixup_f32 v14, v16, v14, v12
	v_pk_mul_f32 v[8:9], v[8:9], v[14:15]
	v_cvt_f32_f16_e32 v14, v69
	v_cvt_pk_f16_f32 v8, v8, v9
	v_cvt_f32_f16_sdwa v9, v69 dst_sel:DWORD dst_unused:UNUSED_PAD src0_sel:WORD_1
	v_mul_f32_e32 v12, 0xbfb8aa3b, v14
	v_exp_f32_e32 v12, v12
	v_mul_f32_e32 v13, 0xbfb8aa3b, v9
	v_exp_f32_e32 v13, v13
	s_nop 0
	v_pk_add_f32 v[12:13], v[12:13], 1.0 op_sel_hi:[1,0]
	s_nop 0
	v_div_scale_f32 v15, s[4:5], v13, v13, v9
	v_rcp_f32_e32 v16, v15
	s_nop 0
	v_fma_f32 v17, -v15, v16, 1.0
	v_fmac_f32_e32 v16, v17, v16
	v_div_scale_f32 v17, vcc, v9, v13, v9
	v_mul_f32_e32 v18, v17, v16
	v_fma_f32 v19, -v15, v18, v17
	v_fmac_f32_e32 v18, v19, v16
	v_fma_f32 v15, -v15, v18, v17
	v_div_fmas_f32 v15, v15, v16, v18
	v_div_fixup_f32 v13, v15, v13, v9
	v_div_scale_f32 v9, s[4:5], v12, v12, v14
	v_rcp_f32_e32 v15, v9
	s_nop 0
	v_fma_f32 v16, -v9, v15, 1.0
	v_fmac_f32_e32 v15, v16, v15
	v_div_scale_f32 v16, vcc, v14, v12, v14
	v_mul_f32_e32 v17, v16, v15
	v_fma_f32 v18, -v9, v17, v16
	v_fmac_f32_e32 v17, v18, v15
	v_fma_f32 v9, -v9, v17, v16
	v_div_fmas_f32 v9, v9, v15, v17
	v_div_fixup_f32 v12, v9, v12, v14
	v_pk_mul_f32 v[10:11], v[10:11], v[12:13]
	s_nop 0
	v_cvt_pk_f16_f32 v9, v10, v11
	global_store_dwordx2 v[28:29], v[8:9], off offset:160
	s_waitcnt vmcnt(7)
	v_cvt_f32_f16_sdwa v12, v70 dst_sel:DWORD dst_unused:UNUSED_PAD src0_sel:WORD_1
	v_cvt_f32_f16_e32 v8, v70
	v_mul_f32_e32 v11, 0xbfb8aa3b, v12
	v_mul_f32_e32 v10, 0xbfb8aa3b, v8
	v_exp_f32_e32 v10, v10
	v_exp_f32_e32 v11, v11
	s_nop 0
	v_pk_add_f32 v[10:11], v[10:11], 1.0 op_sel_hi:[1,0]
	s_nop 0
	v_div_scale_f32 v13, s[4:5], v11, v11, v12
	v_rcp_f32_e32 v14, v13
	s_nop 0
	v_fma_f32 v15, -v13, v14, 1.0
	v_fmac_f32_e32 v14, v15, v14
	v_div_scale_f32 v15, vcc, v12, v11, v12
	v_mul_f32_e32 v16, v15, v14
	v_fma_f32 v17, -v13, v16, v15
	v_fmac_f32_e32 v16, v17, v14
	v_fma_f32 v13, -v13, v16, v15
	v_div_fmas_f32 v13, v13, v14, v16
	v_div_fixup_f32 v11, v13, v11, v12
	v_div_scale_f32 v12, s[4:5], v10, v10, v8
	v_rcp_f32_e32 v13, v12
	s_nop 0
	v_fma_f32 v14, -v12, v13, 1.0
	v_fmac_f32_e32 v13, v14, v13
	v_div_scale_f32 v14, vcc, v8, v10, v8
	v_mul_f32_e32 v15, v14, v13
	v_fma_f32 v16, -v12, v15, v14
	v_fmac_f32_e32 v15, v16, v13
	v_fma_f32 v12, -v12, v15, v14
	v_div_fmas_f32 v12, v12, v13, v15
	v_div_fixup_f32 v10, v12, v10, v8
	v_pk_mul_f32 v[4:5], v[4:5], v[10:11]
	v_cvt_f32_f16_e32 v10, v71
	v_cvt_pk_f16_f32 v4, v4, v5
	v_cvt_f32_f16_sdwa v5, v71 dst_sel:DWORD dst_unused:UNUSED_PAD src0_sel:WORD_1
	v_mul_f32_e32 v8, 0xbfb8aa3b, v10
	v_exp_f32_e32 v8, v8
	v_mul_f32_e32 v9, 0xbfb8aa3b, v5
	v_exp_f32_e32 v9, v9
	s_nop 0
	v_pk_add_f32 v[8:9], v[8:9], 1.0 op_sel_hi:[1,0]
	s_nop 0
	v_div_scale_f32 v11, s[4:5], v9, v9, v5
	v_rcp_f32_e32 v12, v11
	s_nop 0
	v_fma_f32 v13, -v11, v12, 1.0
	v_fmac_f32_e32 v12, v13, v12
	v_div_scale_f32 v13, vcc, v5, v9, v5
	v_mul_f32_e32 v14, v13, v12
	v_fma_f32 v15, -v11, v14, v13
	v_fmac_f32_e32 v14, v15, v12
	v_fma_f32 v11, -v11, v14, v13
	v_div_fmas_f32 v11, v11, v12, v14
	v_div_fixup_f32 v9, v11, v9, v5
	v_div_scale_f32 v5, s[4:5], v8, v8, v10
	v_rcp_f32_e32 v11, v5
	s_nop 0
	v_fma_f32 v12, -v5, v11, 1.0
	v_fmac_f32_e32 v11, v12, v11
	v_div_scale_f32 v12, vcc, v10, v8, v10
	v_mul_f32_e32 v13, v12, v11
	v_fma_f32 v14, -v5, v13, v12
	v_fmac_f32_e32 v13, v14, v11
	v_fma_f32 v5, -v5, v13, v12
	v_div_fmas_f32 v5, v5, v11, v13
	v_div_fixup_f32 v8, v5, v8, v10
	v_pk_mul_f32 v[6:7], v[6:7], v[8:9]
	s_nop 0
	v_cvt_pk_f16_f32 v5, v6, v7
	global_store_dwordx2 v[28:29], v[4:5], off offset:192
	s_waitcnt vmcnt(7)
	v_cvt_f32_f16_sdwa v8, v72 dst_sel:DWORD dst_unused:UNUSED_PAD src0_sel:WORD_1
	v_cvt_f32_f16_e32 v4, v72
	v_mul_f32_e32 v7, 0xbfb8aa3b, v8
	v_mul_f32_e32 v6, 0xbfb8aa3b, v4
	v_exp_f32_e32 v6, v6
	v_exp_f32_e32 v7, v7
	s_nop 0
	v_pk_add_f32 v[6:7], v[6:7], 1.0 op_sel_hi:[1,0]
	s_nop 0
	v_div_scale_f32 v9, s[4:5], v7, v7, v8
	v_rcp_f32_e32 v10, v9
	s_nop 0
	v_fma_f32 v11, -v9, v10, 1.0
	v_fmac_f32_e32 v10, v11, v10
	v_div_scale_f32 v11, vcc, v8, v7, v8
	v_mul_f32_e32 v12, v11, v10
	v_fma_f32 v13, -v9, v12, v11
	v_fmac_f32_e32 v12, v13, v10
	v_fma_f32 v9, -v9, v12, v11
	v_div_fmas_f32 v9, v9, v10, v12
	v_div_fixup_f32 v7, v9, v7, v8
	v_div_scale_f32 v8, s[4:5], v6, v6, v4
	v_rcp_f32_e32 v9, v8
	s_nop 0
	v_fma_f32 v10, -v8, v9, 1.0
	v_fmac_f32_e32 v9, v10, v9
	v_div_scale_f32 v10, vcc, v4, v6, v4
	v_mul_f32_e32 v11, v10, v9
	v_fma_f32 v12, -v8, v11, v10
	v_fmac_f32_e32 v11, v12, v9
	v_fma_f32 v8, -v8, v11, v10
	v_div_fmas_f32 v8, v8, v9, v11
	v_div_fixup_f32 v6, v8, v6, v4
	v_pk_mul_f32 v[0:1], v[0:1], v[6:7]
	v_cvt_f32_f16_e32 v6, v73
	v_cvt_pk_f16_f32 v0, v0, v1
	v_cvt_f32_f16_sdwa v1, v73 dst_sel:DWORD dst_unused:UNUSED_PAD src0_sel:WORD_1
	v_mul_f32_e32 v4, 0xbfb8aa3b, v6
	v_exp_f32_e32 v4, v4
	v_mul_f32_e32 v5, 0xbfb8aa3b, v1
	v_exp_f32_e32 v5, v5
	s_nop 0
	v_pk_add_f32 v[4:5], v[4:5], 1.0 op_sel_hi:[1,0]
	s_nop 0
	v_div_scale_f32 v7, s[4:5], v5, v5, v1
	v_rcp_f32_e32 v8, v7
	s_nop 0
	v_fma_f32 v9, -v7, v8, 1.0
	v_fmac_f32_e32 v8, v9, v8
	v_div_scale_f32 v9, vcc, v1, v5, v1
	v_mul_f32_e32 v10, v9, v8
	v_fma_f32 v11, -v7, v10, v9
	v_fmac_f32_e32 v10, v11, v8
	v_fma_f32 v7, -v7, v10, v9
	v_div_fmas_f32 v7, v7, v8, v10
	v_div_fixup_f32 v5, v7, v5, v1
	v_div_scale_f32 v1, s[4:5], v4, v4, v6
	v_rcp_f32_e32 v7, v1
	s_nop 0
	v_fma_f32 v8, -v1, v7, 1.0
	v_fmac_f32_e32 v7, v8, v7
	v_div_scale_f32 v8, vcc, v6, v4, v6
	v_mul_f32_e32 v9, v8, v7
	v_fma_f32 v10, -v1, v9, v8
	v_fmac_f32_e32 v9, v10, v7
	v_fma_f32 v1, -v1, v9, v8
	v_div_fmas_f32 v1, v1, v7, v9
	v_div_fixup_f32 v4, v1, v4, v6
	v_pk_mul_f32 v[2:3], v[2:3], v[4:5]
	s_nop 0
	v_cvt_pk_f16_f32 v1, v2, v3
	global_store_dwordx2 v[28:29], v[0:1], off offset:224

.Lgin_loop:
	s_waitcnt vmcnt(4)
	s_barrier
	ds_read_b128 v[230:233], v175 offset:0
	ds_read_b128 v[234:237], v175 offset:2048
	ds_read_b128 v[238:241], v175 offset:4096
	ds_read_b128 v[242:245], v175 offset:6144
	ds_read_b128 v[136:139], v177 offset:0
	ds_read_b128 v[140:143], v177 offset:2048
	ds_read_b128 v[144:147], v177 offset:4096
	ds_read_b128 v[148:151], v177 offset:6144
	ds_read_b128 v[182:185], v176 offset:16384
	ds_read_b128 v[186:189], v176 offset:18432
	ds_read_b128 v[190:193], v176 offset:20480
	ds_read_b128 v[194:197], v176 offset:22528
	s_add_u32 m0, s11, 0xc000
	s_waitcnt lgkmcnt(3)
	v_mfma_f32_16x16x32_f16 v[124:127], v[230:233], v[182:185], v[124:127]
	v_mfma_f32_16x16x32_f16 v[92:95], v[234:237], v[182:185], v[92:95]
	v_mfma_f32_16x16x32_f16 v[60:63], v[238:241], v[182:185], v[60:63]
	v_mfma_f32_16x16x32_f16 v[28:31], v[242:245], v[182:185], v[28:31]
	global_load_lds_dwordx4 v128, s[6:7]
	s_barrier
	ds_read_b128 v[198:201], v178 offset:16384
	ds_read_b128 v[202:205], v178 offset:18432
	ds_read_b128 v[222:225], v178 offset:20480
	ds_read_b128 v[226:229], v178 offset:22528
	s_add_u32 m0, s11, 0xd000
	s_waitcnt lgkmcnt(6)
	v_mfma_f32_16x16x32_f16 v[120:123], v[230:233], v[186:189], v[120:123]
	v_mfma_f32_16x16x32_f16 v[88:91], v[234:237], v[186:189], v[88:91]
	v_mfma_f32_16x16x32_f16 v[56:59], v[238:241], v[186:189], v[56:59]
	v_mfma_f32_16x16x32_f16 v[24:27], v[242:245], v[186:189], v[24:27]
	global_load_lds_dwordx4 v129, s[6:7]
	s_add_u32 m0, s11, 0xe000
	s_waitcnt lgkmcnt(5)
	v_mfma_f32_16x16x32_f16 v[116:119], v[230:233], v[190:193], v[116:119]
	v_mfma_f32_16x16x32_f16 v[84:87], v[234:237], v[190:193], v[84:87]
	v_mfma_f32_16x16x32_f16 v[52:55], v[238:241], v[190:193], v[52:55]
	v_mfma_f32_16x16x32_f16 v[20:23], v[242:245], v[190:193], v[20:23]
	global_load_lds_dwordx4 v132, s[6:7]
	s_add_u32 m0, s11, 0xf000
	s_waitcnt lgkmcnt(4)
	v_mfma_f32_16x16x32_f16 v[112:115], v[230:233], v[194:197], v[112:115]
	v_mfma_f32_16x16x32_f16 v[80:83], v[234:237], v[194:197], v[80:83]
	v_mfma_f32_16x16x32_f16 v[48:51], v[238:241], v[194:197], v[48:51]
	v_mfma_f32_16x16x32_f16 v[16:19], v[242:245], v[194:197], v[16:19]
	global_load_lds_dwordx4 v133, s[6:7]
	s_add_u32 m0, s11, 0x0
	s_waitcnt lgkmcnt(3)
	v_mfma_f32_16x16x32_f16 v[124:127], v[136:139], v[198:201], v[124:127]
	v_mfma_f32_16x16x32_f16 v[92:95], v[140:143], v[198:201], v[92:95]
	v_mfma_f32_16x16x32_f16 v[60:63], v[144:147], v[198:201], v[60:63]
	v_mfma_f32_16x16x32_f16 v[28:31], v[148:151], v[198:201], v[28:31]
	global_load_lds_dwordx4 v128, s[4:5]
	s_add_u32 m0, s11, 0x1000
	s_waitcnt lgkmcnt(2)
	v_mfma_f32_16x16x32_f16 v[120:123], v[136:139], v[202:205], v[120:123]
	v_mfma_f32_16x16x32_f16 v[88:91], v[140:143], v[202:205], v[88:91]
	v_mfma_f32_16x16x32_f16 v[56:59], v[144:147], v[202:205], v[56:59]
	v_mfma_f32_16x16x32_f16 v[24:27], v[148:151], v[202:205], v[24:27]
	global_load_lds_dwordx4 v129, s[4:5]
	s_add_u32 m0, s11, 0x2000
	s_waitcnt lgkmcnt(1)
	v_mfma_f32_16x16x32_f16 v[116:119], v[136:139], v[222:225], v[116:119]
	v_mfma_f32_16x16x32_f16 v[84:87], v[140:143], v[222:225], v[84:87]
	v_mfma_f32_16x16x32_f16 v[52:55], v[144:147], v[222:225], v[52:55]
	v_mfma_f32_16x16x32_f16 v[20:23], v[148:151], v[222:225], v[20:23]
	global_load_lds_dwordx4 v130, s[4:5]
	s_add_u32 m0, s11, 0x3000
	s_waitcnt lgkmcnt(0)
	v_mfma_f32_16x16x32_f16 v[112:115], v[136:139], v[226:229], v[112:115]
	v_mfma_f32_16x16x32_f16 v[80:83], v[140:143], v[226:229], v[80:83]
	v_mfma_f32_16x16x32_f16 v[48:51], v[144:147], v[226:229], v[48:51]
	v_mfma_f32_16x16x32_f16 v[16:19], v[148:151], v[226:229], v[16:19]
	global_load_lds_dwordx4 v131, s[4:5]
	s_add_u32 s6, s6, 128
	s_addc_u32 s7, s7, 0
	s_add_u32 s4, s4, 128
	s_addc_u32 s5, s5, 0
	s_waitcnt vmcnt(8)
	s_barrier
	ds_read_b128 v[182:185], v176 offset:32768
	ds_read_b128 v[186:189], v176 offset:34816
	ds_read_b128 v[190:193], v176 offset:36864
	ds_read_b128 v[194:197], v176 offset:38912
	ds_read_b128 v[198:201], v178 offset:32768
	ds_read_b128 v[202:205], v178 offset:34816
	ds_read_b128 v[222:225], v178 offset:36864
	ds_read_b128 v[226:229], v178 offset:38912
	s_add_u32 m0, s11, 0x4000
	s_waitcnt lgkmcnt(7)
	v_mfma_f32_16x16x32_f16 v[108:111], v[230:233], v[182:185], v[108:111]
	v_mfma_f32_16x16x32_f16 v[76:79], v[234:237], v[182:185], v[76:79]
	v_mfma_f32_16x16x32_f16 v[44:47], v[238:241], v[182:185], v[44:47]
	v_mfma_f32_16x16x32_f16 v[12:15], v[242:245], v[182:185], v[12:15]
	global_load_lds_dwordx4 v128, s[18:19]
	s_add_u32 m0, s11, 0x5000
	s_waitcnt lgkmcnt(6)
	v_mfma_f32_16x16x32_f16 v[104:107], v[230:233], v[186:189], v[104:107]
	v_mfma_f32_16x16x32_f16 v[72:75], v[234:237], v[186:189], v[72:75]
	v_mfma_f32_16x16x32_f16 v[40:43], v[238:241], v[186:189], v[40:43]
	v_mfma_f32_16x16x32_f16 v[8:11], v[242:245], v[186:189], v[8:11]
	global_load_lds_dwordx4 v129, s[18:19]
	s_add_u32 m0, s11, 0x6000
	s_waitcnt lgkmcnt(5)
	v_mfma_f32_16x16x32_f16 v[100:103], v[230:233], v[190:193], v[100:103]
	v_mfma_f32_16x16x32_f16 v[68:71], v[234:237], v[190:193], v[68:71]
	v_mfma_f32_16x16x32_f16 v[36:39], v[238:241], v[190:193], v[36:39]
	v_mfma_f32_16x16x32_f16 v[4:7], v[242:245], v[190:193], v[4:7]
	global_load_lds_dwordx4 v132, s[18:19]
	s_add_u32 m0, s11, 0x7000
	s_waitcnt lgkmcnt(4)
	v_mfma_f32_16x16x32_f16 v[96:99], v[230:233], v[194:197], v[96:99]
	v_mfma_f32_16x16x32_f16 v[64:67], v[234:237], v[194:197], v[64:67]
	v_mfma_f32_16x16x32_f16 v[32:35], v[238:241], v[194:197], v[32:35]
	v_mfma_f32_16x16x32_f16 v[0:3], v[242:245], v[194:197], v[0:3]
	global_load_lds_dwordx4 v133, s[18:19]
	s_waitcnt lgkmcnt(3)
	v_mfma_f32_16x16x32_f16 v[108:111], v[136:139], v[198:201], v[108:111]
	v_mfma_f32_16x16x32_f16 v[76:79], v[140:143], v[198:201], v[76:79]
	v_mfma_f32_16x16x32_f16 v[44:47], v[144:147], v[198:201], v[44:47]
	v_mfma_f32_16x16x32_f16 v[12:15], v[148:151], v[198:201], v[12:15]
	s_waitcnt lgkmcnt(2)
	v_mfma_f32_16x16x32_f16 v[104:107], v[136:139], v[202:205], v[104:107]
	v_mfma_f32_16x16x32_f16 v[72:75], v[140:143], v[202:205], v[72:75]
	v_mfma_f32_16x16x32_f16 v[40:43], v[144:147], v[202:205], v[40:43]
	v_mfma_f32_16x16x32_f16 v[8:11], v[148:151], v[202:205], v[8:11]
	s_waitcnt lgkmcnt(1)
	v_mfma_f32_16x16x32_f16 v[100:103], v[136:139], v[222:225], v[100:103]
	v_mfma_f32_16x16x32_f16 v[68:71], v[140:143], v[222:225], v[68:71]
	v_mfma_f32_16x16x32_f16 v[36:39], v[144:147], v[222:225], v[36:39]
	v_mfma_f32_16x16x32_f16 v[4:7], v[148:151], v[222:225], v[4:7]
	s_waitcnt lgkmcnt(0)
	v_mfma_f32_16x16x32_f16 v[96:99], v[136:139], v[226:229], v[96:99]
	v_mfma_f32_16x16x32_f16 v[64:67], v[140:143], v[226:229], v[64:67]
	v_mfma_f32_16x16x32_f16 v[32:35], v[144:147], v[226:229], v[32:35]
	v_mfma_f32_16x16x32_f16 v[0:3], v[148:151], v[226:229], v[0:3]
	s_add_u32 s18, s18, 128
	s_addc_u32 s19, s19, 0
	s_waitcnt vmcnt(4)
	s_barrier
	ds_read_b128 v[230:233], v175 offset:0
	ds_read_b128 v[234:237], v175 offset:2048
	ds_read_b128 v[238:241], v175 offset:4096
	ds_read_b128 v[242:245], v175 offset:6144
	ds_read_b128 v[136:139], v177 offset:0
	ds_read_b128 v[140:143], v177 offset:2048
	ds_read_b128 v[144:147], v177 offset:4096
	ds_read_b128 v[148:151], v177 offset:6144
	ds_read_b128 v[182:185], v176 offset:49152
	ds_read_b128 v[186:189], v176 offset:51200
	ds_read_b128 v[190:193], v176 offset:53248
	ds_read_b128 v[194:197], v176 offset:55296
	s_add_u32 m0, s11, 0x8000
	s_waitcnt lgkmcnt(3)
	v_mfma_f32_16x16x32_f16 v[124:127], v[230:233], v[182:185], v[124:127]
	v_mfma_f32_16x16x32_f16 v[92:95], v[234:237], v[182:185], v[92:95]
	v_mfma_f32_16x16x32_f16 v[60:63], v[238:241], v[182:185], v[60:63]
	v_mfma_f32_16x16x32_f16 v[28:31], v[242:245], v[182:185], v[28:31]
	global_load_lds_dwordx4 v128, s[6:7]
	s_barrier
	ds_read_b128 v[198:201], v178 offset:49152
	ds_read_b128 v[202:205], v178 offset:51200
	ds_read_b128 v[222:225], v178 offset:53248
	ds_read_b128 v[226:229], v178 offset:55296
	s_add_u32 m0, s11, 0x9000
	s_waitcnt lgkmcnt(6)
	v_mfma_f32_16x16x32_f16 v[120:123], v[230:233], v[186:189], v[120:123]
	v_mfma_f32_16x16x32_f16 v[88:91], v[234:237], v[186:189], v[88:91]
	v_mfma_f32_16x16x32_f16 v[56:59], v[238:241], v[186:189], v[56:59]
	v_mfma_f32_16x16x32_f16 v[24:27], v[242:245], v[186:189], v[24:27]
	global_load_lds_dwordx4 v129, s[6:7]
	s_add_u32 m0, s11, 0xa000
	s_waitcnt lgkmcnt(5)
	v_mfma_f32_16x16x32_f16 v[116:119], v[230:233], v[190:193], v[116:119]
	v_mfma_f32_16x16x32_f16 v[84:87], v[234:237], v[190:193], v[84:87]
	v_mfma_f32_16x16x32_f16 v[52:55], v[238:241], v[190:193], v[52:55]
	v_mfma_f32_16x16x32_f16 v[20:23], v[242:245], v[190:193], v[20:23]
	global_load_lds_dwordx4 v132, s[6:7]
	s_add_u32 m0, s11, 0xb000
	s_waitcnt lgkmcnt(4)
	v_mfma_f32_16x16x32_f16 v[112:115], v[230:233], v[194:197], v[112:115]
	v_mfma_f32_16x16x32_f16 v[80:83], v[234:237], v[194:197], v[80:83]
	v_mfma_f32_16x16x32_f16 v[48:51], v[238:241], v[194:197], v[48:51]
	v_mfma_f32_16x16x32_f16 v[16:19], v[242:245], v[194:197], v[16:19]
	global_load_lds_dwordx4 v133, s[6:7]
	s_add_u32 m0, s11, 0x0
	s_waitcnt lgkmcnt(3)
	v_mfma_f32_16x16x32_f16 v[124:127], v[136:139], v[198:201], v[124:127]
	v_mfma_f32_16x16x32_f16 v[92:95], v[140:143], v[198:201], v[92:95]
	v_mfma_f32_16x16x32_f16 v[60:63], v[144:147], v[198:201], v[60:63]
	v_mfma_f32_16x16x32_f16 v[28:31], v[148:151], v[198:201], v[28:31]
	global_load_lds_dwordx4 v128, s[4:5]
	s_add_u32 m0, s11, 0x1000
	s_waitcnt lgkmcnt(2)
	v_mfma_f32_16x16x32_f16 v[120:123], v[136:139], v[202:205], v[120:123]
	v_mfma_f32_16x16x32_f16 v[88:91], v[140:143], v[202:205], v[88:91]
	v_mfma_f32_16x16x32_f16 v[56:59], v[144:147], v[202:205], v[56:59]
	v_mfma_f32_16x16x32_f16 v[24:27], v[148:151], v[202:205], v[24:27]
	global_load_lds_dwordx4 v129, s[4:5]
	s_add_u32 m0, s11, 0x2000
	s_waitcnt lgkmcnt(1)
	v_mfma_f32_16x16x32_f16 v[116:119], v[136:139], v[222:225], v[116:119]
	v_mfma_f32_16x16x32_f16 v[84:87], v[140:143], v[222:225], v[84:87]
	v_mfma_f32_16x16x32_f16 v[52:55], v[144:147], v[222:225], v[52:55]
	v_mfma_f32_16x16x32_f16 v[20:23], v[148:151], v[222:225], v[20:23]
	global_load_lds_dwordx4 v130, s[4:5]
	s_add_u32 m0, s11, 0x3000
	s_waitcnt lgkmcnt(0)
	v_mfma_f32_16x16x32_f16 v[112:115], v[136:139], v[226:229], v[112:115]
	v_mfma_f32_16x16x32_f16 v[80:83], v[140:143], v[226:229], v[80:83]
	v_mfma_f32_16x16x32_f16 v[48:51], v[144:147], v[226:229], v[48:51]
	v_mfma_f32_16x16x32_f16 v[16:19], v[148:151], v[226:229], v[16:19]
	global_load_lds_dwordx4 v131, s[4:5]
	s_add_u32 s6, s6, 128
	s_addc_u32 s7, s7, 0
	s_add_u32 s4, s4, 128
	s_addc_u32 s5, s5, 0
	s_waitcnt vmcnt(8)
	s_barrier
	ds_read_b128 v[182:185], v176 offset:16384
	ds_read_b128 v[186:189], v176 offset:18432
	ds_read_b128 v[190:193], v176 offset:20480
	ds_read_b128 v[194:197], v176 offset:22528
	ds_read_b128 v[198:201], v178 offset:16384
	ds_read_b128 v[202:205], v178 offset:18432
	ds_read_b128 v[222:225], v178 offset:20480
	ds_read_b128 v[226:229], v178 offset:22528
	s_add_u32 m0, s11, 0xc000
	s_waitcnt lgkmcnt(7)
	v_mfma_f32_16x16x32_f16 v[108:111], v[230:233], v[182:185], v[108:111]
	v_mfma_f32_16x16x32_f16 v[76:79], v[234:237], v[182:185], v[76:79]
	v_mfma_f32_16x16x32_f16 v[44:47], v[238:241], v[182:185], v[44:47]
	v_mfma_f32_16x16x32_f16 v[12:15], v[242:245], v[182:185], v[12:15]
	global_load_lds_dwordx4 v128, s[18:19]
	s_add_u32 m0, s11, 0xd000
	s_waitcnt lgkmcnt(6)
	v_mfma_f32_16x16x32_f16 v[104:107], v[230:233], v[186:189], v[104:107]
	v_mfma_f32_16x16x32_f16 v[72:75], v[234:237], v[186:189], v[72:75]
	v_mfma_f32_16x16x32_f16 v[40:43], v[238:241], v[186:189], v[40:43]
	v_mfma_f32_16x16x32_f16 v[8:11], v[242:245], v[186:189], v[8:11]
	global_load_lds_dwordx4 v129, s[18:19]
	s_add_u32 m0, s11, 0xe000
	s_waitcnt lgkmcnt(5)
	v_mfma_f32_16x16x32_f16 v[100:103], v[230:233], v[190:193], v[100:103]
	v_mfma_f32_16x16x32_f16 v[68:71], v[234:237], v[190:193], v[68:71]
	v_mfma_f32_16x16x32_f16 v[36:39], v[238:241], v[190:193], v[36:39]
	v_mfma_f32_16x16x32_f16 v[4:7], v[242:245], v[190:193], v[4:7]
	global_load_lds_dwordx4 v132, s[18:19]
	s_add_u32 m0, s11, 0xf000
	s_waitcnt lgkmcnt(4)
	v_mfma_f32_16x16x32_f16 v[96:99], v[230:233], v[194:197], v[96:99]
	v_mfma_f32_16x16x32_f16 v[64:67], v[234:237], v[194:197], v[64:67]
	v_mfma_f32_16x16x32_f16 v[32:35], v[238:241], v[194:197], v[32:35]
	v_mfma_f32_16x16x32_f16 v[0:3], v[242:245], v[194:197], v[0:3]
	global_load_lds_dwordx4 v133, s[18:19]
	s_waitcnt lgkmcnt(3)
	v_mfma_f32_16x16x32_f16 v[108:111], v[136:139], v[198:201], v[108:111]
	v_mfma_f32_16x16x32_f16 v[76:79], v[140:143], v[198:201], v[76:79]
	v_mfma_f32_16x16x32_f16 v[44:47], v[144:147], v[198:201], v[44:47]
	v_mfma_f32_16x16x32_f16 v[12:15], v[148:151], v[198:201], v[12:15]
	s_waitcnt lgkmcnt(2)
	v_mfma_f32_16x16x32_f16 v[104:107], v[136:139], v[202:205], v[104:107]
	v_mfma_f32_16x16x32_f16 v[72:75], v[140:143], v[202:205], v[72:75]
	v_mfma_f32_16x16x32_f16 v[40:43], v[144:147], v[202:205], v[40:43]
	v_mfma_f32_16x16x32_f16 v[8:11], v[148:151], v[202:205], v[8:11]
	s_waitcnt lgkmcnt(1)
	v_mfma_f32_16x16x32_f16 v[100:103], v[136:139], v[222:225], v[100:103]
	v_mfma_f32_16x16x32_f16 v[68:71], v[140:143], v[222:225], v[68:71]
	v_mfma_f32_16x16x32_f16 v[36:39], v[144:147], v[222:225], v[36:39]
	v_mfma_f32_16x16x32_f16 v[4:7], v[148:151], v[222:225], v[4:7]
	s_waitcnt lgkmcnt(0)
	v_mfma_f32_16x16x32_f16 v[96:99], v[136:139], v[226:229], v[96:99]
	v_mfma_f32_16x16x32_f16 v[64:67], v[140:143], v[226:229], v[64:67]
	v_mfma_f32_16x16x32_f16 v[32:35], v[144:147], v[226:229], v[32:35]
	v_mfma_f32_16x16x32_f16 v[0:3], v[148:151], v[226:229], v[0:3]
	s_add_u32 s18, s18, 128
	s_addc_u32 s19, s19, 0
	s_waitcnt vmcnt(4)
	s_barrier
	ds_read_b128 v[230:233], v175 offset:0
	ds_read_b128 v[234:237], v175 offset:2048
	ds_read_b128 v[238:241], v175 offset:4096
	ds_read_b128 v[242:245], v175 offset:6144
	ds_read_b128 v[136:139], v177 offset:0
	ds_read_b128 v[140:143], v177 offset:2048
	ds_read_b128 v[144:147], v177 offset:4096
	ds_read_b128 v[148:151], v177 offset:6144
	ds_read_b128 v[182:185], v176 offset:32768
	ds_read_b128 v[186:189], v176 offset:34816
	ds_read_b128 v[190:193], v176 offset:36864
	ds_read_b128 v[194:197], v176 offset:38912
	s_add_u32 m0, s11, 0x4000
	s_waitcnt lgkmcnt(3)
	v_mfma_f32_16x16x32_f16 v[124:127], v[230:233], v[182:185], v[124:127]
	v_mfma_f32_16x16x32_f16 v[92:95], v[234:237], v[182:185], v[92:95]
	v_mfma_f32_16x16x32_f16 v[60:63], v[238:241], v[182:185], v[60:63]
	v_mfma_f32_16x16x32_f16 v[28:31], v[242:245], v[182:185], v[28:31]
	global_load_lds_dwordx4 v128, s[6:7]
	s_barrier
	ds_read_b128 v[198:201], v178 offset:32768
	ds_read_b128 v[202:205], v178 offset:34816
	ds_read_b128 v[222:225], v178 offset:36864
	ds_read_b128 v[226:229], v178 offset:38912
	s_add_u32 m0, s11, 0x5000
	s_waitcnt lgkmcnt(6)
	v_mfma_f32_16x16x32_f16 v[120:123], v[230:233], v[186:189], v[120:123]
	v_mfma_f32_16x16x32_f16 v[88:91], v[234:237], v[186:189], v[88:91]
	v_mfma_f32_16x16x32_f16 v[56:59], v[238:241], v[186:189], v[56:59]
	v_mfma_f32_16x16x32_f16 v[24:27], v[242:245], v[186:189], v[24:27]
	global_load_lds_dwordx4 v129, s[6:7]
	s_add_u32 m0, s11, 0x6000
	s_waitcnt lgkmcnt(5)
	v_mfma_f32_16x16x32_f16 v[116:119], v[230:233], v[190:193], v[116:119]
	v_mfma_f32_16x16x32_f16 v[84:87], v[234:237], v[190:193], v[84:87]
	v_mfma_f32_16x16x32_f16 v[52:55], v[238:241], v[190:193], v[52:55]
	v_mfma_f32_16x16x32_f16 v[20:23], v[242:245], v[190:193], v[20:23]
	global_load_lds_dwordx4 v132, s[6:7]
	s_add_u32 m0, s11, 0x7000
	s_waitcnt lgkmcnt(4)
	v_mfma_f32_16x16x32_f16 v[112:115], v[230:233], v[194:197], v[112:115]
	v_mfma_f32_16x16x32_f16 v[80:83], v[234:237], v[194:197], v[80:83]
	v_mfma_f32_16x16x32_f16 v[48:51], v[238:241], v[194:197], v[48:51]
	v_mfma_f32_16x16x32_f16 v[16:19], v[242:245], v[194:197], v[16:19]
	global_load_lds_dwordx4 v133, s[6:7]
	s_add_u32 m0, s11, 0x0
	s_waitcnt lgkmcnt(3)
	v_mfma_f32_16x16x32_f16 v[124:127], v[136:139], v[198:201], v[124:127]
	v_mfma_f32_16x16x32_f16 v[92:95], v[140:143], v[198:201], v[92:95]
	v_mfma_f32_16x16x32_f16 v[60:63], v[144:147], v[198:201], v[60:63]
	v_mfma_f32_16x16x32_f16 v[28:31], v[148:151], v[198:201], v[28:31]
	global_load_lds_dwordx4 v128, s[4:5]
	s_add_u32 m0, s11, 0x1000
	s_waitcnt lgkmcnt(2)
	v_mfma_f32_16x16x32_f16 v[120:123], v[136:139], v[202:205], v[120:123]
	v_mfma_f32_16x16x32_f16 v[88:91], v[140:143], v[202:205], v[88:91]
	v_mfma_f32_16x16x32_f16 v[56:59], v[144:147], v[202:205], v[56:59]
	v_mfma_f32_16x16x32_f16 v[24:27], v[148:151], v[202:205], v[24:27]
	global_load_lds_dwordx4 v129, s[4:5]
	s_add_u32 m0, s11, 0x2000
	s_waitcnt lgkmcnt(1)
	v_mfma_f32_16x16x32_f16 v[116:119], v[136:139], v[222:225], v[116:119]
	v_mfma_f32_16x16x32_f16 v[84:87], v[140:143], v[222:225], v[84:87]
	v_mfma_f32_16x16x32_f16 v[52:55], v[144:147], v[222:225], v[52:55]
	v_mfma_f32_16x16x32_f16 v[20:23], v[148:151], v[222:225], v[20:23]
	global_load_lds_dwordx4 v130, s[4:5]
	s_add_u32 m0, s11, 0x3000
	s_waitcnt lgkmcnt(0)
	v_mfma_f32_16x16x32_f16 v[112:115], v[136:139], v[226:229], v[112:115]
	v_mfma_f32_16x16x32_f16 v[80:83], v[140:143], v[226:229], v[80:83]
	v_mfma_f32_16x16x32_f16 v[48:51], v[144:147], v[226:229], v[48:51]
	v_mfma_f32_16x16x32_f16 v[16:19], v[148:151], v[226:229], v[16:19]
	global_load_lds_dwordx4 v131, s[4:5]
	s_add_u32 s6, s6, 128
	s_addc_u32 s7, s7, 0
	s_add_u32 s4, s4, 128
	s_addc_u32 s5, s5, 0
	s_waitcnt vmcnt(8)
	s_barrier
	ds_read_b128 v[182:185], v176 offset:49152
	ds_read_b128 v[186:189], v176 offset:51200
	ds_read_b128 v[190:193], v176 offset:53248
	ds_read_b128 v[194:197], v176 offset:55296
	ds_read_b128 v[198:201], v178 offset:49152
	ds_read_b128 v[202:205], v178 offset:51200
	ds_read_b128 v[222:225], v178 offset:53248
	ds_read_b128 v[226:229], v178 offset:55296
	s_add_u32 m0, s11, 0x8000
	s_waitcnt lgkmcnt(7)
	v_mfma_f32_16x16x32_f16 v[108:111], v[230:233], v[182:185], v[108:111]
	v_mfma_f32_16x16x32_f16 v[76:79], v[234:237], v[182:185], v[76:79]
	v_mfma_f32_16x16x32_f16 v[44:47], v[238:241], v[182:185], v[44:47]
	v_mfma_f32_16x16x32_f16 v[12:15], v[242:245], v[182:185], v[12:15]
	global_load_lds_dwordx4 v128, s[18:19]
	s_add_u32 m0, s11, 0x9000
	s_waitcnt lgkmcnt(6)
	v_mfma_f32_16x16x32_f16 v[104:107], v[230:233], v[186:189], v[104:107]
	v_mfma_f32_16x16x32_f16 v[72:75], v[234:237], v[186:189], v[72:75]
	v_mfma_f32_16x16x32_f16 v[40:43], v[238:241], v[186:189], v[40:43]
	v_mfma_f32_16x16x32_f16 v[8:11], v[242:245], v[186:189], v[8:11]
	global_load_lds_dwordx4 v129, s[18:19]
	s_add_u32 m0, s11, 0xa000
	s_waitcnt lgkmcnt(5)
	v_mfma_f32_16x16x32_f16 v[100:103], v[230:233], v[190:193], v[100:103]
	v_mfma_f32_16x16x32_f16 v[68:71], v[234:237], v[190:193], v[68:71]
	v_mfma_f32_16x16x32_f16 v[36:39], v[238:241], v[190:193], v[36:39]
	v_mfma_f32_16x16x32_f16 v[4:7], v[242:245], v[190:193], v[4:7]
	global_load_lds_dwordx4 v132, s[18:19]
	s_add_u32 m0, s11, 0xb000
	s_waitcnt lgkmcnt(4)
	v_mfma_f32_16x16x32_f16 v[96:99], v[230:233], v[194:197], v[96:99]
	v_mfma_f32_16x16x32_f16 v[64:67], v[234:237], v[194:197], v[64:67]
	v_mfma_f32_16x16x32_f16 v[32:35], v[238:241], v[194:197], v[32:35]
	v_mfma_f32_16x16x32_f16 v[0:3], v[242:245], v[194:197], v[0:3]
	global_load_lds_dwordx4 v133, s[18:19]
	s_waitcnt lgkmcnt(3)
	v_mfma_f32_16x16x32_f16 v[108:111], v[136:139], v[198:201], v[108:111]
	v_mfma_f32_16x16x32_f16 v[76:79], v[140:143], v[198:201], v[76:79]
	v_mfma_f32_16x16x32_f16 v[44:47], v[144:147], v[198:201], v[44:47]
	v_mfma_f32_16x16x32_f16 v[12:15], v[148:151], v[198:201], v[12:15]
	s_waitcnt lgkmcnt(2)
	v_mfma_f32_16x16x32_f16 v[104:107], v[136:139], v[202:205], v[104:107]
	v_mfma_f32_16x16x32_f16 v[72:75], v[140:143], v[202:205], v[72:75]
	v_mfma_f32_16x16x32_f16 v[40:43], v[144:147], v[202:205], v[40:43]
	v_mfma_f32_16x16x32_f16 v[8:11], v[148:151], v[202:205], v[8:11]
	s_waitcnt lgkmcnt(1)
	v_mfma_f32_16x16x32_f16 v[100:103], v[136:139], v[222:225], v[100:103]
	v_mfma_f32_16x16x32_f16 v[68:71], v[140:143], v[222:225], v[68:71]
	v_mfma_f32_16x16x32_f16 v[36:39], v[144:147], v[222:225], v[36:39]
	v_mfma_f32_16x16x32_f16 v[4:7], v[148:151], v[222:225], v[4:7]
	s_waitcnt lgkmcnt(0)
	v_mfma_f32_16x16x32_f16 v[96:99], v[136:139], v[226:229], v[96:99]
	v_mfma_f32_16x16x32_f16 v[64:67], v[140:143], v[226:229], v[64:67]
	v_mfma_f32_16x16x32_f16 v[32:35], v[144:147], v[226:229], v[32:35]
	v_mfma_f32_16x16x32_f16 v[0:3], v[148:151], v[226:229], v[0:3]
	s_add_u32 s18, s18, 128
	s_addc_u32 s19, s19, 0
	s_add_i32 s10, s10, 1
	s_cmp_lt_u32 s10, 10
	s_cbranch_scc1 .Lgin_loop
	s_waitcnt vmcnt(4)
	s_barrier
	ds_read_b128 v[230:233], v175 offset:0
	ds_read_b128 v[234:237], v175 offset:2048
	ds_read_b128 v[238:241], v175 offset:4096
	ds_read_b128 v[242:245], v175 offset:6144
	ds_read_b128 v[136:139], v177 offset:0
	ds_read_b128 v[140:143], v177 offset:2048
	ds_read_b128 v[144:147], v177 offset:4096
	ds_read_b128 v[148:151], v177 offset:6144
	ds_read_b128 v[182:185], v176 offset:16384
	ds_read_b128 v[186:189], v176 offset:18432
	ds_read_b128 v[190:193], v176 offset:20480
	ds_read_b128 v[194:197], v176 offset:22528
	s_add_u32 m0, s11, 0xc000
	s_waitcnt lgkmcnt(3)
	v_mfma_f32_16x16x32_f16 v[124:127], v[230:233], v[182:185], v[124:127]
	v_mfma_f32_16x16x32_f16 v[92:95], v[234:237], v[182:185], v[92:95]
	v_mfma_f32_16x16x32_f16 v[60:63], v[238:241], v[182:185], v[60:63]
	v_mfma_f32_16x16x32_f16 v[28:31], v[242:245], v[182:185], v[28:31]
	global_load_lds_dwordx4 v128, s[6:7]
	s_barrier
	ds_read_b128 v[198:201], v178 offset:16384
	ds_read_b128 v[202:205], v178 offset:18432
	ds_read_b128 v[222:225], v178 offset:20480
	ds_read_b128 v[226:229], v178 offset:22528
	s_add_u32 m0, s11, 0xd000
	s_waitcnt lgkmcnt(6)
	v_mfma_f32_16x16x32_f16 v[120:123], v[230:233], v[186:189], v[120:123]
	v_mfma_f32_16x16x32_f16 v[88:91], v[234:237], v[186:189], v[88:91]
	v_mfma_f32_16x16x32_f16 v[56:59], v[238:241], v[186:189], v[56:59]
	v_mfma_f32_16x16x32_f16 v[24:27], v[242:245], v[186:189], v[24:27]
	global_load_lds_dwordx4 v129, s[6:7]
	s_add_u32 m0, s11, 0xe000
	s_waitcnt lgkmcnt(5)
	v_mfma_f32_16x16x32_f16 v[116:119], v[230:233], v[190:193], v[116:119]
	v_mfma_f32_16x16x32_f16 v[84:87], v[234:237], v[190:193], v[84:87]
	v_mfma_f32_16x16x32_f16 v[52:55], v[238:241], v[190:193], v[52:55]
	v_mfma_f32_16x16x32_f16 v[20:23], v[242:245], v[190:193], v[20:23]
	global_load_lds_dwordx4 v132, s[6:7]
	s_add_u32 m0, s11, 0xf000
	s_waitcnt lgkmcnt(4)
	v_mfma_f32_16x16x32_f16 v[112:115], v[230:233], v[194:197], v[112:115]
	v_mfma_f32_16x16x32_f16 v[80:83], v[234:237], v[194:197], v[80:83]
	v_mfma_f32_16x16x32_f16 v[48:51], v[238:241], v[194:197], v[48:51]
	v_mfma_f32_16x16x32_f16 v[16:19], v[242:245], v[194:197], v[16:19]
	global_load_lds_dwordx4 v133, s[6:7]
	s_add_u32 m0, s11, 0x0
	s_waitcnt lgkmcnt(3)
	v_mfma_f32_16x16x32_f16 v[124:127], v[136:139], v[198:201], v[124:127]
	v_mfma_f32_16x16x32_f16 v[92:95], v[140:143], v[198:201], v[92:95]
	v_mfma_f32_16x16x32_f16 v[60:63], v[144:147], v[198:201], v[60:63]
	v_mfma_f32_16x16x32_f16 v[28:31], v[148:151], v[198:201], v[28:31]
	global_load_lds_dwordx4 v128, s[4:5]
	s_add_u32 m0, s11, 0x1000
	s_waitcnt lgkmcnt(2)
	v_mfma_f32_16x16x32_f16 v[120:123], v[136:139], v[202:205], v[120:123]
	v_mfma_f32_16x16x32_f16 v[88:91], v[140:143], v[202:205], v[88:91]
	v_mfma_f32_16x16x32_f16 v[56:59], v[144:147], v[202:205], v[56:59]
	v_mfma_f32_16x16x32_f16 v[24:27], v[148:151], v[202:205], v[24:27]
	global_load_lds_dwordx4 v129, s[4:5]
	s_add_u32 m0, s11, 0x2000
	s_waitcnt lgkmcnt(1)
	v_mfma_f32_16x16x32_f16 v[116:119], v[136:139], v[222:225], v[116:119]
	v_mfma_f32_16x16x32_f16 v[84:87], v[140:143], v[222:225], v[84:87]
	v_mfma_f32_16x16x32_f16 v[52:55], v[144:147], v[222:225], v[52:55]
	v_mfma_f32_16x16x32_f16 v[20:23], v[148:151], v[222:225], v[20:23]
	global_load_lds_dwordx4 v130, s[4:5]
	s_add_u32 m0, s11, 0x3000
	s_waitcnt lgkmcnt(0)
	v_mfma_f32_16x16x32_f16 v[112:115], v[136:139], v[226:229], v[112:115]
	v_mfma_f32_16x16x32_f16 v[80:83], v[140:143], v[226:229], v[80:83]
	v_mfma_f32_16x16x32_f16 v[48:51], v[144:147], v[226:229], v[48:51]
	v_mfma_f32_16x16x32_f16 v[16:19], v[148:151], v[226:229], v[16:19]
	global_load_lds_dwordx4 v131, s[4:5]
	s_add_u32 s6, s6, 128
	s_addc_u32 s7, s7, 0
	s_add_u32 s4, s4, 128
	s_addc_u32 s5, s5, 0
	s_waitcnt vmcnt(8)
	s_barrier
	ds_read_b128 v[182:185], v176 offset:32768
	ds_read_b128 v[186:189], v176 offset:34816
	ds_read_b128 v[190:193], v176 offset:36864
	ds_read_b128 v[194:197], v176 offset:38912
	ds_read_b128 v[198:201], v178 offset:32768
	ds_read_b128 v[202:205], v178 offset:34816
	ds_read_b128 v[222:225], v178 offset:36864
	ds_read_b128 v[226:229], v178 offset:38912
	s_add_u32 m0, s11, 0x4000
	s_waitcnt lgkmcnt(7)
	v_mfma_f32_16x16x32_f16 v[108:111], v[230:233], v[182:185], v[108:111]
	v_mfma_f32_16x16x32_f16 v[76:79], v[234:237], v[182:185], v[76:79]
	v_mfma_f32_16x16x32_f16 v[44:47], v[238:241], v[182:185], v[44:47]
	v_mfma_f32_16x16x32_f16 v[12:15], v[242:245], v[182:185], v[12:15]
	global_load_lds_dwordx4 v128, s[18:19]
	s_add_u32 m0, s11, 0x5000
	s_waitcnt lgkmcnt(6)
	v_mfma_f32_16x16x32_f16 v[104:107], v[230:233], v[186:189], v[104:107]
	v_mfma_f32_16x16x32_f16 v[72:75], v[234:237], v[186:189], v[72:75]
	v_mfma_f32_16x16x32_f16 v[40:43], v[238:241], v[186:189], v[40:43]
	v_mfma_f32_16x16x32_f16 v[8:11], v[242:245], v[186:189], v[8:11]
	global_load_lds_dwordx4 v129, s[18:19]
	s_add_u32 m0, s11, 0x6000
	s_waitcnt lgkmcnt(5)
	v_mfma_f32_16x16x32_f16 v[100:103], v[230:233], v[190:193], v[100:103]
	v_mfma_f32_16x16x32_f16 v[68:71], v[234:237], v[190:193], v[68:71]
	v_mfma_f32_16x16x32_f16 v[36:39], v[238:241], v[190:193], v[36:39]
	v_mfma_f32_16x16x32_f16 v[4:7], v[242:245], v[190:193], v[4:7]
	global_load_lds_dwordx4 v132, s[18:19]
	s_add_u32 m0, s11, 0x7000
	s_waitcnt lgkmcnt(4)
	v_mfma_f32_16x16x32_f16 v[96:99], v[230:233], v[194:197], v[96:99]
	v_mfma_f32_16x16x32_f16 v[64:67], v[234:237], v[194:197], v[64:67]
	v_mfma_f32_16x16x32_f16 v[32:35], v[238:241], v[194:197], v[32:35]
	v_mfma_f32_16x16x32_f16 v[0:3], v[242:245], v[194:197], v[0:3]
	global_load_lds_dwordx4 v133, s[18:19]
	s_waitcnt lgkmcnt(3)
	v_mfma_f32_16x16x32_f16 v[108:111], v[136:139], v[198:201], v[108:111]
	v_mfma_f32_16x16x32_f16 v[76:79], v[140:143], v[198:201], v[76:79]
	v_mfma_f32_16x16x32_f16 v[44:47], v[144:147], v[198:201], v[44:47]
	v_mfma_f32_16x16x32_f16 v[12:15], v[148:151], v[198:201], v[12:15]
	s_waitcnt lgkmcnt(2)
	v_mfma_f32_16x16x32_f16 v[104:107], v[136:139], v[202:205], v[104:107]
	v_mfma_f32_16x16x32_f16 v[72:75], v[140:143], v[202:205], v[72:75]
	v_mfma_f32_16x16x32_f16 v[40:43], v[144:147], v[202:205], v[40:43]
	v_mfma_f32_16x16x32_f16 v[8:11], v[148:151], v[202:205], v[8:11]
	s_waitcnt lgkmcnt(1)
	v_mfma_f32_16x16x32_f16 v[100:103], v[136:139], v[222:225], v[100:103]
	v_mfma_f32_16x16x32_f16 v[68:71], v[140:143], v[222:225], v[68:71]
	v_mfma_f32_16x16x32_f16 v[36:39], v[144:147], v[222:225], v[36:39]
	v_mfma_f32_16x16x32_f16 v[4:7], v[148:151], v[222:225], v[4:7]
	s_waitcnt lgkmcnt(0)
	v_mfma_f32_16x16x32_f16 v[96:99], v[136:139], v[226:229], v[96:99]
	v_mfma_f32_16x16x32_f16 v[64:67], v[140:143], v[226:229], v[64:67]
	v_mfma_f32_16x16x32_f16 v[32:35], v[144:147], v[226:229], v[32:35]
	v_mfma_f32_16x16x32_f16 v[0:3], v[148:151], v[226:229], v[0:3]
	s_add_u32 s18, s18, 128
	s_addc_u32 s19, s19, 0
	s_waitcnt vmcnt(4)
	s_barrier
	ds_read_b128 v[230:233], v175 offset:0
	ds_read_b128 v[234:237], v175 offset:2048
	ds_read_b128 v[238:241], v175 offset:4096
	ds_read_b128 v[242:245], v175 offset:6144
	ds_read_b128 v[136:139], v177 offset:0
	ds_read_b128 v[140:143], v177 offset:2048
	ds_read_b128 v[144:147], v177 offset:4096
	ds_read_b128 v[148:151], v177 offset:6144
	ds_read_b128 v[182:185], v176 offset:49152
	ds_read_b128 v[186:189], v176 offset:51200
	ds_read_b128 v[190:193], v176 offset:53248
	ds_read_b128 v[194:197], v176 offset:55296
	s_waitcnt lgkmcnt(3)
	v_mfma_f32_16x16x32_f16 v[124:127], v[230:233], v[182:185], v[124:127]
	v_mfma_f32_16x16x32_f16 v[92:95], v[234:237], v[182:185], v[92:95]
	v_mfma_f32_16x16x32_f16 v[60:63], v[238:241], v[182:185], v[60:63]
	v_mfma_f32_16x16x32_f16 v[28:31], v[242:245], v[182:185], v[28:31]
	s_barrier
	ds_read_b128 v[198:201], v178 offset:49152
	ds_read_b128 v[202:205], v178 offset:51200
	ds_read_b128 v[222:225], v178 offset:53248
	ds_read_b128 v[226:229], v178 offset:55296
	s_waitcnt lgkmcnt(6)
	v_mfma_f32_16x16x32_f16 v[120:123], v[230:233], v[186:189], v[120:123]
	v_mfma_f32_16x16x32_f16 v[88:91], v[234:237], v[186:189], v[88:91]
	v_mfma_f32_16x16x32_f16 v[56:59], v[238:241], v[186:189], v[56:59]
	v_mfma_f32_16x16x32_f16 v[24:27], v[242:245], v[186:189], v[24:27]
	s_waitcnt lgkmcnt(5)
	v_mfma_f32_16x16x32_f16 v[116:119], v[230:233], v[190:193], v[116:119]
	v_mfma_f32_16x16x32_f16 v[84:87], v[234:237], v[190:193], v[84:87]
	v_mfma_f32_16x16x32_f16 v[52:55], v[238:241], v[190:193], v[52:55]
	v_mfma_f32_16x16x32_f16 v[20:23], v[242:245], v[190:193], v[20:23]
	s_waitcnt lgkmcnt(4)
	v_mfma_f32_16x16x32_f16 v[112:115], v[230:233], v[194:197], v[112:115]
	v_mfma_f32_16x16x32_f16 v[80:83], v[234:237], v[194:197], v[80:83]
	v_mfma_f32_16x16x32_f16 v[48:51], v[238:241], v[194:197], v[48:51]
	v_mfma_f32_16x16x32_f16 v[16:19], v[242:245], v[194:197], v[16:19]
	s_waitcnt lgkmcnt(3)
	v_mfma_f32_16x16x32_f16 v[124:127], v[136:139], v[198:201], v[124:127]
	v_mfma_f32_16x16x32_f16 v[92:95], v[140:143], v[198:201], v[92:95]
	v_mfma_f32_16x16x32_f16 v[60:63], v[144:147], v[198:201], v[60:63]
	v_mfma_f32_16x16x32_f16 v[28:31], v[148:151], v[198:201], v[28:31]
	s_waitcnt lgkmcnt(2)
	v_mfma_f32_16x16x32_f16 v[120:123], v[136:139], v[202:205], v[120:123]
	v_mfma_f32_16x16x32_f16 v[88:91], v[140:143], v[202:205], v[88:91]
	v_mfma_f32_16x16x32_f16 v[56:59], v[144:147], v[202:205], v[56:59]
	v_mfma_f32_16x16x32_f16 v[24:27], v[148:151], v[202:205], v[24:27]
	s_waitcnt lgkmcnt(1)
	v_mfma_f32_16x16x32_f16 v[116:119], v[136:139], v[222:225], v[116:119]
	v_mfma_f32_16x16x32_f16 v[84:87], v[140:143], v[222:225], v[84:87]
	v_mfma_f32_16x16x32_f16 v[52:55], v[144:147], v[222:225], v[52:55]
	v_mfma_f32_16x16x32_f16 v[20:23], v[148:151], v[222:225], v[20:23]
	s_waitcnt lgkmcnt(0)
	v_mfma_f32_16x16x32_f16 v[112:115], v[136:139], v[226:229], v[112:115]
	v_mfma_f32_16x16x32_f16 v[80:83], v[140:143], v[226:229], v[80:83]
	v_mfma_f32_16x16x32_f16 v[48:51], v[144:147], v[226:229], v[48:51]
	v_mfma_f32_16x16x32_f16 v[16:19], v[148:151], v[226:229], v[16:19]
	s_waitcnt vmcnt(0)
	s_barrier
	ds_read_b128 v[182:185], v176 offset:16384
	ds_read_b128 v[186:189], v176 offset:18432
	ds_read_b128 v[190:193], v176 offset:20480
	ds_read_b128 v[194:197], v176 offset:22528
	ds_read_b128 v[198:201], v178 offset:16384
	ds_read_b128 v[202:205], v178 offset:18432
	ds_read_b128 v[222:225], v178 offset:20480
	ds_read_b128 v[226:229], v178 offset:22528
	s_waitcnt lgkmcnt(7)
	v_mfma_f32_16x16x32_f16 v[108:111], v[230:233], v[182:185], v[108:111]
	v_mfma_f32_16x16x32_f16 v[76:79], v[234:237], v[182:185], v[76:79]
	v_mfma_f32_16x16x32_f16 v[44:47], v[238:241], v[182:185], v[44:47]
	v_mfma_f32_16x16x32_f16 v[12:15], v[242:245], v[182:185], v[12:15]
	s_waitcnt lgkmcnt(6)
	v_mfma_f32_16x16x32_f16 v[104:107], v[230:233], v[186:189], v[104:107]
	v_mfma_f32_16x16x32_f16 v[72:75], v[234:237], v[186:189], v[72:75]
	v_mfma_f32_16x16x32_f16 v[40:43], v[238:241], v[186:189], v[40:43]
	v_mfma_f32_16x16x32_f16 v[8:11], v[242:245], v[186:189], v[8:11]
	s_waitcnt lgkmcnt(5)
	v_mfma_f32_16x16x32_f16 v[100:103], v[230:233], v[190:193], v[100:103]
	v_mfma_f32_16x16x32_f16 v[68:71], v[234:237], v[190:193], v[68:71]
	v_mfma_f32_16x16x32_f16 v[36:39], v[238:241], v[190:193], v[36:39]
	v_mfma_f32_16x16x32_f16 v[4:7], v[242:245], v[190:193], v[4:7]
	s_waitcnt lgkmcnt(4)
	v_mfma_f32_16x16x32_f16 v[96:99], v[230:233], v[194:197], v[96:99]
	v_mfma_f32_16x16x32_f16 v[64:67], v[234:237], v[194:197], v[64:67]
	v_mfma_f32_16x16x32_f16 v[32:35], v[238:241], v[194:197], v[32:35]
	v_mfma_f32_16x16x32_f16 v[0:3], v[242:245], v[194:197], v[0:3]
	s_waitcnt lgkmcnt(3)
	v_mfma_f32_16x16x32_f16 v[108:111], v[136:139], v[198:201], v[108:111]
	v_mfma_f32_16x16x32_f16 v[76:79], v[140:143], v[198:201], v[76:79]
	v_mfma_f32_16x16x32_f16 v[44:47], v[144:147], v[198:201], v[44:47]
	v_mfma_f32_16x16x32_f16 v[12:15], v[148:151], v[198:201], v[12:15]
	s_waitcnt lgkmcnt(2)
	v_mfma_f32_16x16x32_f16 v[104:107], v[136:139], v[202:205], v[104:107]
	v_mfma_f32_16x16x32_f16 v[72:75], v[140:143], v[202:205], v[72:75]
	v_mfma_f32_16x16x32_f16 v[40:43], v[144:147], v[202:205], v[40:43]
	v_mfma_f32_16x16x32_f16 v[8:11], v[148:151], v[202:205], v[8:11]
	s_waitcnt lgkmcnt(1)
	v_mfma_f32_16x16x32_f16 v[100:103], v[136:139], v[222:225], v[100:103]
	v_mfma_f32_16x16x32_f16 v[68:71], v[140:143], v[222:225], v[68:71]
	v_mfma_f32_16x16x32_f16 v[36:39], v[144:147], v[222:225], v[36:39]
	v_mfma_f32_16x16x32_f16 v[4:7], v[148:151], v[222:225], v[4:7]
	s_waitcnt lgkmcnt(0)
	v_mfma_f32_16x16x32_f16 v[96:99], v[136:139], v[226:229], v[96:99]
	v_mfma_f32_16x16x32_f16 v[64:67], v[140:143], v[226:229], v[64:67]
	v_mfma_f32_16x16x32_f16 v[32:35], v[144:147], v[226:229], v[32:35]
	v_mfma_f32_16x16x32_f16 v[0:3], v[148:151], v[226:229], v[0:3]
	s_nop 7
	s_cmpk_lt_u32 s9, 0x620
	s_cbranch_scc0 .Lgin_cls_lat
	s_cmp_lt_u32 s16, 4
	s_cbranch_scc1 .Lgin_plain
	s_sub_u32 s4, s16, 8
	s_cmp_lt_u32 s4, 28
	s_cbranch_scc1 .Lgin_plain
	s_sub_u32 s4, s16, 45
	s_cmp_lt_u32 s4, 3
	s_cbranch_scc1 .Lgin_plain
	s_sub_u32 s4, s16, 4
	s_cmp_lt_u32 s4, 2
	s_cbranch_scc1 .Lgin_kvar
	s_sub_u32 s4, s16, 37
	s_cmp_lt_u32 s4, 3
	s_cbranch_scc1 .Lgin_kvar
	s_sub_u32 s4, s16, 6
	s_cmp_lt_u32 s4, 2
	s_cbranch_scc1 .Lgin_vvar
	s_sub_u32 s4, s16, 41
	s_cmp_lt_u32 s4, 3
	s_cbranch_scc1 .Lgin_vvar
	s_branch .Lgin_notplain
.Lgin_cls_lat:
	s_sub_u32 s4, s16, 8
	s_cmp_lt_u32 s4, 32
	s_cbranch_scc1 .Lgin_plain
	s_sub_u32 s4, s16, 45
	s_cmp_lt_u32 s4, 3
	s_cbranch_scc1 .Lgin_plain
	s_sub_u32 s4, s16, 6
	s_cmp_lt_u32 s4, 2
	s_cbranch_scc1 .Lgin_vvar
	s_sub_u32 s4, s16, 41
	s_cmp_lt_u32 s4, 3
	s_cbranch_scc1 .Lgin_vvar
	s_branch .Lgin_notplain

.Lgin_vvar:
	s_barrier
	s_cmp_lt_u32 s16, 8
	s_movk_i32 s6, 0x1410
	s_cselect_b32 s6, 0x300, s6
	s_cselect_b32 s7, 8, 9
	s_lshl_b32 s8, s16, 7
	s_sub_u32 s8, s8, s6
	s_cmpk_lt_u32 s9, 0x620
	s_cbranch_scc0 .Lgin_v_lat
	s_lshr_b32 s10, s0, 8
	s_mov_b32 s19, 8
	s_mov_b32 s18, 0
	s_cmp_lt_u32 s16, 8
	s_mov_b32 s6, 0x10e5f700
	s_cselect_b32 s6, 0x1085f700, s6
	s_branch .Lgin_v_base
.Lgin_v_lat:
	s_sub_u32 s10, s0, 0x2000
	s_and_b32 s18, s10, 0x3ff
	s_lshr_b32 s10, s10, 10
	s_mov_b32 s19, 10
	s_cmp_lt_u32 s16, 8
	s_mov_b32 s6, 0x1165f700
	s_cselect_b32 s6, 0x10c5f700, s6
.Lgin_v_base:
	s_lshl_b32 s10, s10, s7
	s_add_u32 s10, s10, s8
	s_lshl_b32 s10, s10, s19
	s_add_u32 s10, s10, s18
	s_lshl_b32 s10, s10, 1
	s_add_u32 s4, s20, s6
	s_addc_u32 s5, s21, 0
	s_add_u32 s4, s4, s10
	s_addc_u32 s5, s5, 0
	s_lshl_b32 s6, 8, s19
	v_lshrrev_b32_e32 v128, 2, v179
	v_add_u32_e32 v130, v128, v173
	v_lshlrev_b32_e32 v130, s19, v130
	v_lshl_add_u32 v131, v166, 3, v174
	v_add_u32_e32 v130, v130, v131
	v_lshlrev_b32_e32 v130, 1, v130
	v_lshrrev_b32_e32 v132, 6, v174
	v_lshrrev_b32_e32 v133, 6, v173
	v_add_u32_e32 v132, v132, v133
	v_mul_u32_u24_e32 v132, 0x4200, v132
	v_mul_u32_u24_e32 v133, 132, v166
	v_lshl_add_u32 v133, v179, 1, v133
	v_add_u32_e32 v133, v132, v133
	v_mul_u32_u24_e32 v129, 1056, v166
	v_lshl_add_u32 v129, v128, 1, v129
	v_add_u32_e32 v132, v132, v129
	s_cmpk_lt_u32 s9, 0x620
	s_cbranch_scc0 .Lgin_v_wr_lat
	s_lshr_b32 s11, s0, 8
	s_lshl_b32 s11, s11, 1
	v_readlane_b32 s18, v255, 43
	s_nop 0
	s_add_u32 s11, s11, s18
	s_lshl_b32 s11, s11, 8
	s_cmp_lt_u32 s16, 8
	s_mov_b32 s18, 41937904
	s_cselect_b32 s18, 29359360, s18
	s_lshl_b32 s10, s16, 7
	s_add_u32 s18, s18, s10
	s_lshl_b32 s11, s11, s7
	s_add_u32 s11, s11, s18
	s_lshl_b32 s11, s11, 2
	s_add_u32 s10, s94, s11
	s_addc_u32 s11, s95, 0
	s_lshl_b32 s18, 64, s7
	v_add_u32_e32 v131, v174, v166
	v_lshlrev_b32_e32 v131, s7, v131
	v_add3_u32 v131, v131, v173, v179
	v_lshlrev_b32_e32 v131, 2, v131
	global_store_dwordx4 v131, v[124:127], s[10:11] nt
	s_nop 1
	v_cvt_pk_f16_f32 v124, v124, v125
	v_cvt_pk_f16_f32 v125, v126, v127
	ds_write_b32 v133, v124 offset:0
	ds_write_b32 v133, v125 offset:4
	global_store_dwordx4 v131, v[92:95], s[10:11] offset:64 nt
	s_nop 1
	v_cvt_pk_f16_f32 v92, v92, v93
	v_cvt_pk_f16_f32 v93, v94, v95
	ds_write_b32 v133, v92 offset:32
	ds_write_b32 v133, v93 offset:36
	global_store_dwordx4 v131, v[60:63], s[10:11] offset:128 nt
	s_nop 1
	v_cvt_pk_f16_f32 v60, v60, v61
	v_cvt_pk_f16_f32 v61, v62, v63
	ds_write_b32 v133, v60 offset:64
	ds_write_b32 v133, v61 offset:68
	global_store_dwordx4 v131, v[28:31], s[10:11] offset:192 nt
	s_nop 1
	v_cvt_pk_f16_f32 v28, v28, v29
	v_cvt_pk_f16_f32 v29, v30, v31
	ds_write_b32 v133, v28 offset:96
	ds_write_b32 v133, v29 offset:100
	s_add_u32 s10, s10, s18
	s_addc_u32 s11, s11, 0
	global_store_dwordx4 v131, v[120:123], s[10:11] nt
	s_nop 1
	v_cvt_pk_f16_f32 v120, v120, v121
	v_cvt_pk_f16_f32 v121, v122, v123
	ds_write_b32 v133, v120 offset:2112
	ds_write_b32 v133, v121 offset:2116
	global_store_dwordx4 v131, v[88:91], s[10:11] offset:64 nt
	s_nop 1
	v_cvt_pk_f16_f32 v88, v88, v89
	v_cvt_pk_f16_f32 v89, v90, v91
	ds_write_b32 v133, v88 offset:2144
	ds_write_b32 v133, v89 offset:2148
	global_store_dwordx4 v131, v[56:59], s[10:11] offset:128 nt
	s_nop 1
	v_cvt_pk_f16_f32 v56, v56, v57
	v_cvt_pk_f16_f32 v57, v58, v59
	ds_write_b32 v133, v56 offset:2176
	ds_write_b32 v133, v57 offset:2180
	global_store_dwordx4 v131, v[24:27], s[10:11] offset:192 nt
	s_nop 1
	v_cvt_pk_f16_f32 v24, v24, v25
	v_cvt_pk_f16_f32 v25, v26, v27
	ds_write_b32 v133, v24 offset:2208
	ds_write_b32 v133, v25 offset:2212
	s_add_u32 s10, s10, s18
	s_addc_u32 s11, s11, 0
	global_store_dwordx4 v131, v[116:119], s[10:11] nt
	s_nop 1
	v_cvt_pk_f16_f32 v116, v116, v117
	v_cvt_pk_f16_f32 v117, v118, v119
	ds_write_b32 v133, v116 offset:4224
	ds_write_b32 v133, v117 offset:4228
	global_store_dwordx4 v131, v[84:87], s[10:11] offset:64 nt
	s_nop 1
	v_cvt_pk_f16_f32 v84, v84, v85
	v_cvt_pk_f16_f32 v85, v86, v87
	ds_write_b32 v133, v84 offset:4256
	ds_write_b32 v133, v85 offset:4260
	global_store_dwordx4 v131, v[52:55], s[10:11] offset:128 nt
	s_nop 1
	v_cvt_pk_f16_f32 v52, v52, v53
	v_cvt_pk_f16_f32 v53, v54, v55
	ds_write_b32 v133, v52 offset:4288
	ds_write_b32 v133, v53 offset:4292
	global_store_dwordx4 v131, v[20:23], s[10:11] offset:192 nt
	s_nop 1
	v_cvt_pk_f16_f32 v20, v20, v21
	v_cvt_pk_f16_f32 v21, v22, v23
	ds_write_b32 v133, v20 offset:4320
	ds_write_b32 v133, v21 offset:4324
	s_add_u32 s10, s10, s18
	s_addc_u32 s11, s11, 0
	global_store_dwordx4 v131, v[112:115], s[10:11] nt
	s_nop 1
	v_cvt_pk_f16_f32 v112, v112, v113
	v_cvt_pk_f16_f32 v113, v114, v115
	ds_write_b32 v133, v112 offset:6336
	ds_write_b32 v133, v113 offset:6340
	global_store_dwordx4 v131, v[80:83], s[10:11] offset:64 nt
	s_nop 1
	v_cvt_pk_f16_f32 v80, v80, v81
	v_cvt_pk_f16_f32 v81, v82, v83
	ds_write_b32 v133, v80 offset:6368
	ds_write_b32 v133, v81 offset:6372
	global_store_dwordx4 v131, v[48:51], s[10:11] offset:128 nt
	s_nop 1
	v_cvt_pk_f16_f32 v48, v48, v49
	v_cvt_pk_f16_f32 v49, v50, v51
	ds_write_b32 v133, v48 offset:6400
	ds_write_b32 v133, v49 offset:6404
	global_store_dwordx4 v131, v[16:19], s[10:11] offset:192 nt
	s_nop 1
	v_cvt_pk_f16_f32 v16, v16, v17
	v_cvt_pk_f16_f32 v17, v18, v19
	ds_write_b32 v133, v16 offset:6432
	ds_write_b32 v133, v17 offset:6436
	s_add_u32 s10, s10, s18
	s_addc_u32 s11, s11, 0
	global_store_dwordx4 v131, v[108:111], s[10:11] nt
	s_nop 1
	v_cvt_pk_f16_f32 v108, v108, v109
	v_cvt_pk_f16_f32 v109, v110, v111
	ds_write_b32 v133, v108 offset:8448
	ds_write_b32 v133, v109 offset:8452
	global_store_dwordx4 v131, v[76:79], s[10:11] offset:64 nt
	s_nop 1
	v_cvt_pk_f16_f32 v76, v76, v77
	v_cvt_pk_f16_f32 v77, v78, v79
	ds_write_b32 v133, v76 offset:8480
	ds_write_b32 v133, v77 offset:8484
	global_store_dwordx4 v131, v[44:47], s[10:11] offset:128 nt
	s_nop 1
	v_cvt_pk_f16_f32 v44, v44, v45
	v_cvt_pk_f16_f32 v45, v46, v47
	ds_write_b32 v133, v44 offset:8512
	ds_write_b32 v133, v45 offset:8516
	global_store_dwordx4 v131, v[12:15], s[10:11] offset:192 nt
	s_nop 1
	v_cvt_pk_f16_f32 v12, v12, v13
	v_cvt_pk_f16_f32 v13, v14, v15
	ds_write_b32 v133, v12 offset:8544
	ds_write_b32 v133, v13 offset:8548
	s_add_u32 s10, s10, s18
	s_addc_u32 s11, s11, 0
	global_store_dwordx4 v131, v[104:107], s[10:11] nt
	s_nop 1
	v_cvt_pk_f16_f32 v104, v104, v105
	v_cvt_pk_f16_f32 v105, v106, v107
	ds_write_b32 v133, v104 offset:10560
	ds_write_b32 v133, v105 offset:10564
	global_store_dwordx4 v131, v[72:75], s[10:11] offset:64 nt
	s_nop 1
	v_cvt_pk_f16_f32 v72, v72, v73
	v_cvt_pk_f16_f32 v73, v74, v75
	ds_write_b32 v133, v72 offset:10592
	ds_write_b32 v133, v73 offset:10596
	global_store_dwordx4 v131, v[40:43], s[10:11] offset:128 nt
	s_nop 1
	v_cvt_pk_f16_f32 v40, v40, v41
	v_cvt_pk_f16_f32 v41, v42, v43
	ds_write_b32 v133, v40 offset:10624
	ds_write_b32 v133, v41 offset:10628
	global_store_dwordx4 v131, v[8:11], s[10:11] offset:192 nt
	s_nop 1
	v_cvt_pk_f16_f32 v8, v8, v9
	v_cvt_pk_f16_f32 v9, v10, v11
	ds_write_b32 v133, v8 offset:10656
	ds_write_b32 v133, v9 offset:10660
	s_add_u32 s10, s10, s18
	s_addc_u32 s11, s11, 0
	global_store_dwordx4 v131, v[100:103], s[10:11] nt
	s_nop 1
	v_cvt_pk_f16_f32 v100, v100, v101
	v_cvt_pk_f16_f32 v101, v102, v103
	ds_write_b32 v133, v100 offset:12672
	ds_write_b32 v133, v101 offset:12676
	global_store_dwordx4 v131, v[68:71], s[10:11] offset:64 nt
	s_nop 1
	v_cvt_pk_f16_f32 v68, v68, v69
	v_cvt_pk_f16_f32 v69, v70, v71
	ds_write_b32 v133, v68 offset:12704
	ds_write_b32 v133, v69 offset:12708
	global_store_dwordx4 v131, v[36:39], s[10:11] offset:128 nt
	s_nop 1
	v_cvt_pk_f16_f32 v36, v36, v37
	v_cvt_pk_f16_f32 v37, v38, v39
	ds_write_b32 v133, v36 offset:12736
	ds_write_b32 v133, v37 offset:12740
	global_store_dwordx4 v131, v[4:7], s[10:11] offset:192 nt
	s_nop 1
	v_cvt_pk_f16_f32 v4, v4, v5
	v_cvt_pk_f16_f32 v5, v6, v7
	ds_write_b32 v133, v4 offset:12768
	ds_write_b32 v133, v5 offset:12772
	s_add_u32 s10, s10, s18
	s_addc_u32 s11, s11, 0
	global_store_dwordx4 v131, v[96:99], s[10:11] nt
	s_nop 1
	v_cvt_pk_f16_f32 v96, v96, v97
	v_cvt_pk_f16_f32 v97, v98, v99
	ds_write_b32 v133, v96 offset:14784
	ds_write_b32 v133, v97 offset:14788
	global_store_dwordx4 v131, v[64:67], s[10:11] offset:64 nt
	s_nop 1
	v_cvt_pk_f16_f32 v64, v64, v65
	v_cvt_pk_f16_f32 v65, v66, v67
	ds_write_b32 v133, v64 offset:14816
	ds_write_b32 v133, v65 offset:14820
	global_store_dwordx4 v131, v[32:35], s[10:11] offset:128 nt
	s_nop 1
	v_cvt_pk_f16_f32 v32, v32, v33
	v_cvt_pk_f16_f32 v33, v34, v35
	ds_write_b32 v133, v32 offset:14848
	ds_write_b32 v133, v33 offset:14852
	global_store_dwordx4 v131, v[0:3], s[10:11] offset:192 nt
	s_nop 1
	v_cvt_pk_f16_f32 v0, v0, v1
	v_cvt_pk_f16_f32 v1, v2, v3
	ds_write_b32 v133, v0 offset:14880
	ds_write_b32 v133, v1 offset:14884
	s_branch .Lgin_v_rd
.Lgin_v_wr_lat:
	v_cvt_pk_f16_f32 v124, v124, v125
	v_cvt_pk_f16_f32 v125, v126, v127
	ds_write_b32 v133, v124 offset:0
	ds_write_b32 v133, v125 offset:4
	v_cvt_pk_f16_f32 v92, v92, v93
	v_cvt_pk_f16_f32 v93, v94, v95
	ds_write_b32 v133, v92 offset:32
	ds_write_b32 v133, v93 offset:36
	v_cvt_pk_f16_f32 v60, v60, v61
	v_cvt_pk_f16_f32 v61, v62, v63
	ds_write_b32 v133, v60 offset:64
	ds_write_b32 v133, v61 offset:68
	v_cvt_pk_f16_f32 v28, v28, v29
	v_cvt_pk_f16_f32 v29, v30, v31
	ds_write_b32 v133, v28 offset:96
	ds_write_b32 v133, v29 offset:100
	v_cvt_pk_f16_f32 v120, v120, v121
	v_cvt_pk_f16_f32 v121, v122, v123
	ds_write_b32 v133, v120 offset:2112
	ds_write_b32 v133, v121 offset:2116
	v_cvt_pk_f16_f32 v88, v88, v89
	v_cvt_pk_f16_f32 v89, v90, v91
	ds_write_b32 v133, v88 offset:2144
	ds_write_b32 v133, v89 offset:2148
	v_cvt_pk_f16_f32 v56, v56, v57
	v_cvt_pk_f16_f32 v57, v58, v59
	ds_write_b32 v133, v56 offset:2176
	ds_write_b32 v133, v57 offset:2180
	v_cvt_pk_f16_f32 v24, v24, v25
	v_cvt_pk_f16_f32 v25, v26, v27
	ds_write_b32 v133, v24 offset:2208
	ds_write_b32 v133, v25 offset:2212
	v_cvt_pk_f16_f32 v116, v116, v117
	v_cvt_pk_f16_f32 v117, v118, v119
	ds_write_b32 v133, v116 offset:4224
	ds_write_b32 v133, v117 offset:4228
	v_cvt_pk_f16_f32 v84, v84, v85
	v_cvt_pk_f16_f32 v85, v86, v87
	ds_write_b32 v133, v84 offset:4256
	ds_write_b32 v133, v85 offset:4260
	v_cvt_pk_f16_f32 v52, v52, v53
	v_cvt_pk_f16_f32 v53, v54, v55
	ds_write_b32 v133, v52 offset:4288
	ds_write_b32 v133, v53 offset:4292
	v_cvt_pk_f16_f32 v20, v20, v21
	v_cvt_pk_f16_f32 v21, v22, v23
	ds_write_b32 v133, v20 offset:4320
	ds_write_b32 v133, v21 offset:4324
	v_cvt_pk_f16_f32 v112, v112, v113
	v_cvt_pk_f16_f32 v113, v114, v115
	ds_write_b32 v133, v112 offset:6336
	ds_write_b32 v133, v113 offset:6340
	v_cvt_pk_f16_f32 v80, v80, v81
	v_cvt_pk_f16_f32 v81, v82, v83
	ds_write_b32 v133, v80 offset:6368
	ds_write_b32 v133, v81 offset:6372
	v_cvt_pk_f16_f32 v48, v48, v49
	v_cvt_pk_f16_f32 v49, v50, v51
	ds_write_b32 v133, v48 offset:6400
	ds_write_b32 v133, v49 offset:6404
	v_cvt_pk_f16_f32 v16, v16, v17
	v_cvt_pk_f16_f32 v17, v18, v19
	ds_write_b32 v133, v16 offset:6432
	ds_write_b32 v133, v17 offset:6436
	v_cvt_pk_f16_f32 v108, v108, v109
	v_cvt_pk_f16_f32 v109, v110, v111
	ds_write_b32 v133, v108 offset:8448
	ds_write_b32 v133, v109 offset:8452
	v_cvt_pk_f16_f32 v76, v76, v77
	v_cvt_pk_f16_f32 v77, v78, v79
	ds_write_b32 v133, v76 offset:8480
	ds_write_b32 v133, v77 offset:8484
	v_cvt_pk_f16_f32 v44, v44, v45
	v_cvt_pk_f16_f32 v45, v46, v47
	ds_write_b32 v133, v44 offset:8512
	ds_write_b32 v133, v45 offset:8516
	v_cvt_pk_f16_f32 v12, v12, v13
	v_cvt_pk_f16_f32 v13, v14, v15
	ds_write_b32 v133, v12 offset:8544
	ds_write_b32 v133, v13 offset:8548
	v_cvt_pk_f16_f32 v104, v104, v105
	v_cvt_pk_f16_f32 v105, v106, v107
	ds_write_b32 v133, v104 offset:10560
	ds_write_b32 v133, v105 offset:10564
	v_cvt_pk_f16_f32 v72, v72, v73
	v_cvt_pk_f16_f32 v73, v74, v75
	ds_write_b32 v133, v72 offset:10592
	ds_write_b32 v133, v73 offset:10596
	v_cvt_pk_f16_f32 v40, v40, v41
	v_cvt_pk_f16_f32 v41, v42, v43
	ds_write_b32 v133, v40 offset:10624
	ds_write_b32 v133, v41 offset:10628
	v_cvt_pk_f16_f32 v8, v8, v9
	v_cvt_pk_f16_f32 v9, v10, v11
	ds_write_b32 v133, v8 offset:10656
	ds_write_b32 v133, v9 offset:10660
	v_cvt_pk_f16_f32 v100, v100, v101
	v_cvt_pk_f16_f32 v101, v102, v103
	ds_write_b32 v133, v100 offset:12672
	ds_write_b32 v133, v101 offset:12676
	v_cvt_pk_f16_f32 v68, v68, v69
	v_cvt_pk_f16_f32 v69, v70, v71
	ds_write_b32 v133, v68 offset:12704
	ds_write_b32 v133, v69 offset:12708
	v_cvt_pk_f16_f32 v36, v36, v37
	v_cvt_pk_f16_f32 v37, v38, v39
	ds_write_b32 v133, v36 offset:12736
	ds_write_b32 v133, v37 offset:12740
	v_cvt_pk_f16_f32 v4, v4, v5
	v_cvt_pk_f16_f32 v5, v6, v7
	ds_write_b32 v133, v4 offset:12768
	ds_write_b32 v133, v5 offset:12772
	v_cvt_pk_f16_f32 v96, v96, v97
	v_cvt_pk_f16_f32 v97, v98, v99
	ds_write_b32 v133, v96 offset:14784
	ds_write_b32 v133, v97 offset:14788
	v_cvt_pk_f16_f32 v64, v64, v65
	v_cvt_pk_f16_f32 v65, v66, v67
	ds_write_b32 v133, v64 offset:14816
	ds_write_b32 v133, v65 offset:14820
	v_cvt_pk_f16_f32 v32, v32, v33
	v_cvt_pk_f16_f32 v33, v34, v35
	ds_write_b32 v133, v32 offset:14848
	ds_write_b32 v133, v33 offset:14852
	v_cvt_pk_f16_f32 v0, v0, v1
	v_cvt_pk_f16_f32 v1, v2, v3
	ds_write_b32 v133, v0 offset:14880
	ds_write_b32 v133, v1 offset:14884
.Lgin_v_rd:
	s_waitcnt lgkmcnt(0)
	ds_read_u16 v150, v132 offset:0
	ds_read_u16 v151, v132 offset:132
	ds_read_u16 v152, v132 offset:264
	ds_read_u16 v153, v132 offset:396
	ds_read_u16 v154, v132 offset:528
	ds_read_u16 v155, v132 offset:660
	ds_read_u16 v156, v132 offset:792
	ds_read_u16 v157, v132 offset:924
	ds_read_u16 v158, v132 offset:8
	ds_read_u16 v159, v132 offset:140
	ds_read_u16 v160, v132 offset:272
	ds_read_u16 v161, v132 offset:404
	ds_read_u16 v162, v132 offset:536
	ds_read_u16 v163, v132 offset:668
	ds_read_u16 v164, v132 offset:800
	ds_read_u16 v165, v132 offset:932
	s_waitcnt lgkmcnt(8)
	v_lshl_or_b32 v0, v151, 16, v150
	v_lshl_or_b32 v1, v153, 16, v152
	v_lshl_or_b32 v2, v155, 16, v154
	v_lshl_or_b32 v3, v157, 16, v156
	global_store_dwordx4 v130, v[0:3], s[4:5]
	s_add_u32 s4, s4, s6
	s_addc_u32 s5, s5, 0
	ds_read_u16 v150, v132 offset:16
	ds_read_u16 v151, v132 offset:148
	ds_read_u16 v152, v132 offset:280
	ds_read_u16 v153, v132 offset:412
	ds_read_u16 v154, v132 offset:544
	ds_read_u16 v155, v132 offset:676
	ds_read_u16 v156, v132 offset:808
	ds_read_u16 v157, v132 offset:940
	s_waitcnt lgkmcnt(8)
	v_lshl_or_b32 v4, v159, 16, v158
	v_lshl_or_b32 v5, v161, 16, v160
	v_lshl_or_b32 v6, v163, 16, v162
	v_lshl_or_b32 v7, v165, 16, v164
	global_store_dwordx4 v130, v[4:7], s[4:5]
	s_add_u32 s4, s4, s6
	s_addc_u32 s5, s5, 0
	ds_read_u16 v158, v132 offset:24
	ds_read_u16 v159, v132 offset:156
	ds_read_u16 v160, v132 offset:288
	ds_read_u16 v161, v132 offset:420
	ds_read_u16 v162, v132 offset:552
	ds_read_u16 v163, v132 offset:684
	ds_read_u16 v164, v132 offset:816
	ds_read_u16 v165, v132 offset:948
	s_waitcnt lgkmcnt(8)
	v_lshl_or_b32 v8, v151, 16, v150
	v_lshl_or_b32 v9, v153, 16, v152
	v_lshl_or_b32 v10, v155, 16, v154
	v_lshl_or_b32 v11, v157, 16, v156
	global_store_dwordx4 v130, v[8:11], s[4:5]
	s_add_u32 s4, s4, s6
	s_addc_u32 s5, s5, 0
	ds_read_u16 v150, v132 offset:32
	ds_read_u16 v151, v132 offset:164
	ds_read_u16 v152, v132 offset:296
	ds_read_u16 v153, v132 offset:428
	ds_read_u16 v154, v132 offset:560
	ds_read_u16 v155, v132 offset:692
	ds_read_u16 v156, v132 offset:824
	ds_read_u16 v157, v132 offset:956
	s_waitcnt lgkmcnt(8)
	v_lshl_or_b32 v12, v159, 16, v158
	v_lshl_or_b32 v13, v161, 16, v160
	v_lshl_or_b32 v14, v163, 16, v162
	v_lshl_or_b32 v15, v165, 16, v164
	global_store_dwordx4 v130, v[12:15], s[4:5]
	s_add_u32 s4, s4, s6
	s_addc_u32 s5, s5, 0
	ds_read_u16 v158, v132 offset:40
	ds_read_u16 v159, v132 offset:172
	ds_read_u16 v160, v132 offset:304
	ds_read_u16 v161, v132 offset:436
	ds_read_u16 v162, v132 offset:568
	ds_read_u16 v163, v132 offset:700
	ds_read_u16 v164, v132 offset:832
	ds_read_u16 v165, v132 offset:964
	s_waitcnt lgkmcnt(8)
	v_lshl_or_b32 v0, v151, 16, v150
	v_lshl_or_b32 v1, v153, 16, v152
	v_lshl_or_b32 v2, v155, 16, v154
	v_lshl_or_b32 v3, v157, 16, v156
	global_store_dwordx4 v130, v[0:3], s[4:5]
	s_add_u32 s4, s4, s6
	s_addc_u32 s5, s5, 0
	ds_read_u16 v150, v132 offset:48
	ds_read_u16 v151, v132 offset:180
	ds_read_u16 v152, v132 offset:312
	ds_read_u16 v153, v132 offset:444
	ds_read_u16 v154, v132 offset:576
	ds_read_u16 v155, v132 offset:708
	ds_read_u16 v156, v132 offset:840
	ds_read_u16 v157, v132 offset:972
	s_waitcnt lgkmcnt(8)
	v_lshl_or_b32 v4, v159, 16, v158
	v_lshl_or_b32 v5, v161, 16, v160
	v_lshl_or_b32 v6, v163, 16, v162
	v_lshl_or_b32 v7, v165, 16, v164
	global_store_dwordx4 v130, v[4:7], s[4:5]
	s_add_u32 s4, s4, s6
	s_addc_u32 s5, s5, 0
	ds_read_u16 v158, v132 offset:56
	ds_read_u16 v159, v132 offset:188
	ds_read_u16 v160, v132 offset:320
	ds_read_u16 v161, v132 offset:452
	ds_read_u16 v162, v132 offset:584
	ds_read_u16 v163, v132 offset:716
	ds_read_u16 v164, v132 offset:848
	ds_read_u16 v165, v132 offset:980
	s_waitcnt lgkmcnt(8)
	v_lshl_or_b32 v8, v151, 16, v150
	v_lshl_or_b32 v9, v153, 16, v152
	v_lshl_or_b32 v10, v155, 16, v154
	v_lshl_or_b32 v11, v157, 16, v156
	global_store_dwordx4 v130, v[8:11], s[4:5]
	s_add_u32 s4, s4, s6
	s_addc_u32 s5, s5, 0
	ds_read_u16 v150, v132 offset:64
	ds_read_u16 v151, v132 offset:196
	ds_read_u16 v152, v132 offset:328
	ds_read_u16 v153, v132 offset:460
	ds_read_u16 v154, v132 offset:592
	ds_read_u16 v155, v132 offset:724
	ds_read_u16 v156, v132 offset:856
	ds_read_u16 v157, v132 offset:988
	s_waitcnt lgkmcnt(8)
	v_lshl_or_b32 v12, v159, 16, v158
	v_lshl_or_b32 v13, v161, 16, v160
	v_lshl_or_b32 v14, v163, 16, v162
	v_lshl_or_b32 v15, v165, 16, v164
	global_store_dwordx4 v130, v[12:15], s[4:5]
	s_add_u32 s4, s4, s6
	s_addc_u32 s5, s5, 0
	ds_read_u16 v158, v132 offset:72
	ds_read_u16 v159, v132 offset:204
	ds_read_u16 v160, v132 offset:336
	ds_read_u16 v161, v132 offset:468
	ds_read_u16 v162, v132 offset:600
	ds_read_u16 v163, v132 offset:732
	ds_read_u16 v164, v132 offset:864
	ds_read_u16 v165, v132 offset:996
	s_waitcnt lgkmcnt(8)
	v_lshl_or_b32 v0, v151, 16, v150
	v_lshl_or_b32 v1, v153, 16, v152
	v_lshl_or_b32 v2, v155, 16, v154
	v_lshl_or_b32 v3, v157, 16, v156
	global_store_dwordx4 v130, v[0:3], s[4:5]
	s_add_u32 s4, s4, s6
	s_addc_u32 s5, s5, 0
	ds_read_u16 v150, v132 offset:80
	ds_read_u16 v151, v132 offset:212
	ds_read_u16 v152, v132 offset:344
	ds_read_u16 v153, v132 offset:476
	ds_read_u16 v154, v132 offset:608
	ds_read_u16 v155, v132 offset:740
	ds_read_u16 v156, v132 offset:872
	ds_read_u16 v157, v132 offset:1004
	s_waitcnt lgkmcnt(8)
	v_lshl_or_b32 v4, v159, 16, v158
	v_lshl_or_b32 v5, v161, 16, v160
	v_lshl_or_b32 v6, v163, 16, v162
	v_lshl_or_b32 v7, v165, 16, v164
	global_store_dwordx4 v130, v[4:7], s[4:5]
	s_add_u32 s4, s4, s6
	s_addc_u32 s5, s5, 0
	ds_read_u16 v158, v132 offset:88
	ds_read_u16 v159, v132 offset:220
	ds_read_u16 v160, v132 offset:352
	ds_read_u16 v161, v132 offset:484
	ds_read_u16 v162, v132 offset:616
	ds_read_u16 v163, v132 offset:748
	ds_read_u16 v164, v132 offset:880
	ds_read_u16 v165, v132 offset:1012
	s_waitcnt lgkmcnt(8)
	v_lshl_or_b32 v8, v151, 16, v150
	v_lshl_or_b32 v9, v153, 16, v152
	v_lshl_or_b32 v10, v155, 16, v154
	v_lshl_or_b32 v11, v157, 16, v156
	global_store_dwordx4 v130, v[8:11], s[4:5]
	s_add_u32 s4, s4, s6
	s_addc_u32 s5, s5, 0
	ds_read_u16 v150, v132 offset:96
	ds_read_u16 v151, v132 offset:228
	ds_read_u16 v152, v132 offset:360
	ds_read_u16 v153, v132 offset:492
	ds_read_u16 v154, v132 offset:624
	ds_read_u16 v155, v132 offset:756
	ds_read_u16 v156, v132 offset:888
	ds_read_u16 v157, v132 offset:1020
	s_waitcnt lgkmcnt(8)
	v_lshl_or_b32 v12, v159, 16, v158
	v_lshl_or_b32 v13, v161, 16, v160
	v_lshl_or_b32 v14, v163, 16, v162
	v_lshl_or_b32 v15, v165, 16, v164
	global_store_dwordx4 v130, v[12:15], s[4:5]
	s_add_u32 s4, s4, s6
	s_addc_u32 s5, s5, 0
	ds_read_u16 v158, v132 offset:104
	ds_read_u16 v159, v132 offset:236
	ds_read_u16 v160, v132 offset:368
	ds_read_u16 v161, v132 offset:500
	ds_read_u16 v162, v132 offset:632
	ds_read_u16 v163, v132 offset:764
	ds_read_u16 v164, v132 offset:896
	ds_read_u16 v165, v132 offset:1028
	s_waitcnt lgkmcnt(8)
	v_lshl_or_b32 v0, v151, 16, v150
	v_lshl_or_b32 v1, v153, 16, v152
	v_lshl_or_b32 v2, v155, 16, v154
	v_lshl_or_b32 v3, v157, 16, v156
	global_store_dwordx4 v130, v[0:3], s[4:5]
	s_add_u32 s4, s4, s6
	s_addc_u32 s5, s5, 0
	ds_read_u16 v150, v132 offset:112
	ds_read_u16 v151, v132 offset:244
	ds_read_u16 v152, v132 offset:376
	ds_read_u16 v153, v132 offset:508
	ds_read_u16 v154, v132 offset:640
	ds_read_u16 v155, v132 offset:772
	ds_read_u16 v156, v132 offset:904
	ds_read_u16 v157, v132 offset:1036
	s_waitcnt lgkmcnt(8)
	v_lshl_or_b32 v4, v159, 16, v158
	v_lshl_or_b32 v5, v161, 16, v160
	v_lshl_or_b32 v6, v163, 16, v162
	v_lshl_or_b32 v7, v165, 16, v164
	global_store_dwordx4 v130, v[4:7], s[4:5]
	s_add_u32 s4, s4, s6
	s_addc_u32 s5, s5, 0
	ds_read_u16 v158, v132 offset:120
	ds_read_u16 v159, v132 offset:252
	ds_read_u16 v160, v132 offset:384
	ds_read_u16 v161, v132 offset:516
	ds_read_u16 v162, v132 offset:648
	ds_read_u16 v163, v132 offset:780
	ds_read_u16 v164, v132 offset:912
	ds_read_u16 v165, v132 offset:1044
	s_waitcnt lgkmcnt(8)
	v_lshl_or_b32 v8, v151, 16, v150
	v_lshl_or_b32 v9, v153, 16, v152
	v_lshl_or_b32 v10, v155, 16, v154
	v_lshl_or_b32 v11, v157, 16, v156
	global_store_dwordx4 v130, v[8:11], s[4:5]
	s_add_u32 s4, s4, s6
	s_addc_u32 s5, s5, 0
	s_waitcnt lgkmcnt(0)
	v_lshl_or_b32 v12, v159, 16, v158
	v_lshl_or_b32 v13, v161, 16, v160
	v_lshl_or_b32 v14, v163, 16, v162
	v_lshl_or_b32 v15, v165, 16, v164
	global_store_dwordx4 v130, v[12:15], s[4:5]
	s_mov_b64 s[50:51], exec
	s_branch .LBB0_315
